# test: P1 output H0 placed in the P region (end of the workspace)
# speedup vs baseline: 1.0089x; 1.0024x over previous
; __device__ __forceinline__ unsigned cvt_pk_bf16(float lo, float hi) { unsigned r; asm volatile("v_cvt_pk_bf16_f32 %0, %1, %2" : "=v"(r) : "v"(lo), "v"(hi)); return r; }
; __device__ __forceinline__ void load_row_f32(const float* p, int lane, f32x4 (&v)[8]) {
; #pragma unroll
;     for (int j = 0; j < 8; ++j) v[j] = *(const f32x4*)(p + 4 * lane + 256 * j);
; }
; __device__ __forceinline__ float sumsq8(const f32x4 (&v)[8]) {
;     float s = 0.f;
; #pragma unroll
;     for (int j = 0; j < 8; ++j) s += (v[j][0] * v[j][0] + v[j][1] * v[j][1]) + (v[j][2] * v[j][2] + v[j][3] * v[j][3]);
;     return wave_sum(s);
; }
; __device__ __forceinline__ void modulate_store(const f32x4 (&v)[8], float rstd, const float* pn, const float* modr, bf16_t* orow, int lane) {
; #pragma unroll
;     for (int j = 0; j < 8; ++j) { const int col = 4 * lane + 256 * j;
;         const f32x4 g = *(const f32x4*)(pn + col), sh = *(const f32x4*)(modr + col), sc = *(const f32x4*)(modr + DM + col);
;         const f32x4 hh = v[j] * rstd * g * (sc + 1.f) + sh;
;         u32x2 w; w.x = cvt_pk_bf16(hh[0], hh[1]); w.y = cvt_pk_bf16(hh[2], hh[3]);
;         *(u32x2*)(orow + col) = w; }
; }
; __global__ void __launch_bounds__(NWAVES * 64, 2) mk_fwd(Args args) {
;     ...
;         for (int row0 = F.gw * 3; row0 < MT; row0 += F.NGW * 3) {
;             f32x4 v[3][8];
; #pragma unroll
;             for (int q = 0; q < 3; ++q) { const int row = row0 + q; const float* src = row < ML ? x + (size_t)row * DM : ctx + (size_t)(row - ML) * DM; load_row_f32(src, F.lane, v[q]); }
; #pragma unroll
;             for (int q = 0; q < 3; ++q) { const int row = row0 + q; const int r = row < ML ? row / SEQ : 8;
;                 const float rstd = __builtin_amdgcn_rsqf(sumsq8(v[q]) * (1.f / DM) + EPS);
;                 modulate_store(v[q], rstd, pre_norm, mod + (size_t)r * 6144, H + (size_t)row * DM, F.lane); }
;         }
.Lp1_np0:
	s_add_i32 s4, s6, 1
	s_cmp_lt_u32 s4, 0x4000
	s_cselect_b32 s10, s68, s72
	s_cselect_b32 s11, s69, s73
	s_cselect_b32 s5, 0, 0x4000
	s_sub_i32 s5, s4, s5
	s_lshl_b32 s5, s5, 13
	s_add_u32 s10, s10, s5
	s_addc_u32 s11, s11, 0
	global_load_dwordx4 v[32:35], v128, s[10:11] offset:0 nt
	global_load_dwordx4 v[36:39], v128, s[10:11] offset:1024 nt
	global_load_dwordx4 v[40:43], v128, s[10:11] offset:2048 nt
	global_load_dwordx4 v[44:47], v128, s[10:11] offset:3072 nt
	global_load_dwordx4 v[48:51], v129, s[10:11] offset:0 nt
	global_load_dwordx4 v[52:55], v129, s[10:11] offset:1024 nt
	global_load_dwordx4 v[56:59], v129, s[10:11] offset:2048 nt
	global_load_dwordx4 v[60:63], v129, s[10:11] offset:3072 nt
	s_waitcnt vmcnt(8)
	v_mul_f32_e32 v140, v0, v0
	v_mul_f32_e32 v141, v1, v1
	v_fmac_f32_e32 v140, v2, v2
	v_fmac_f32_e32 v141, v3, v3
	v_fmac_f32_e32 v140, v4, v4
	v_fmac_f32_e32 v141, v5, v5
	v_fmac_f32_e32 v140, v6, v6
	v_fmac_f32_e32 v141, v7, v7
	v_fmac_f32_e32 v140, v8, v8
	v_fmac_f32_e32 v141, v9, v9
	v_fmac_f32_e32 v140, v10, v10
	v_fmac_f32_e32 v141, v11, v11
	v_fmac_f32_e32 v140, v12, v12
	v_fmac_f32_e32 v141, v13, v13
	v_fmac_f32_e32 v140, v14, v14
	v_fmac_f32_e32 v141, v15, v15
	v_fmac_f32_e32 v140, v16, v16
	v_fmac_f32_e32 v141, v17, v17
	v_fmac_f32_e32 v140, v18, v18
	v_fmac_f32_e32 v141, v19, v19
	v_fmac_f32_e32 v140, v20, v20
	v_fmac_f32_e32 v141, v21, v21
	v_fmac_f32_e32 v140, v22, v22
	v_fmac_f32_e32 v141, v23, v23
	v_fmac_f32_e32 v140, v24, v24
	v_fmac_f32_e32 v141, v25, v25
	v_fmac_f32_e32 v140, v26, v26
	v_fmac_f32_e32 v141, v27, v27
	v_fmac_f32_e32 v140, v28, v28
	v_fmac_f32_e32 v141, v29, v29
	v_fmac_f32_e32 v140, v30, v30
	v_fmac_f32_e32 v141, v31, v31
	v_add_f32_e32 v140, v140, v141
	s_nop 1
	v_add_f32_dpp v142, v140, v140 quad_perm:[1,0,3,2] row_mask:0xf bank_mask:0xf
	s_nop 1
	v_add_f32_dpp v142, v142, v142 quad_perm:[2,3,0,1] row_mask:0xf bank_mask:0xf
	s_nop 1
	v_add_f32_dpp v142, v142, v142 row_half_mirror row_mask:0xf bank_mask:0xf
	s_nop 1
	v_add_f32_dpp v142, v142, v142 row_mirror row_mask:0xf bank_mask:0xf
	s_nop 1
	v_readlane_b32 s20, v142, 0
	v_readlane_b32 s21, v142, 16
	v_readlane_b32 s22, v142, 32
	v_readlane_b32 s23, v142, 48
	s_nop 1
	v_mov_b32_e32 v143, s20
	v_add_f32_e32 v143, s21, v143
	v_add_f32_e32 v143, s22, v143
	v_add_f32_e32 v143, s23, v143
	v_fmamk_f32 v143, v143, 0x3a000000, v131
	v_rsq_f32_e32 v143, v143
	s_nop 0
	s_add_i32 s4, s6, 0
	s_lshl_b32 s5, s4, 12
	s_add_u32 s14, s84, s5
	s_addc_u32 s15, s85, 0
	s_add_u32 s14, s14, 0x1a800000
	s_addc_u32 s15, s15, 0
	v_mul_f32_e32 v136, v143, v0
	v_mul_f32_e32 v137, v143, v1
	v_mul_f32_e32 v138, v143, v2
	v_mul_f32_e32 v139, v143, v3
	v_fma_f32 v136, v136, v64, v96
	v_fma_f32 v137, v137, v65, v97
	v_fma_f32 v138, v138, v66, v98
	v_fma_f32 v139, v139, v67, v99
	v_cvt_pk_bf16_f32 v132, v136, v137
	v_cvt_pk_bf16_f32 v133, v138, v139
	global_store_dwordx2 v130, v[132:133], s[14:15] offset:0
	v_mul_f32_e32 v136, v143, v4
	v_mul_f32_e32 v137, v143, v5
	v_mul_f32_e32 v138, v143, v6
	v_mul_f32_e32 v139, v143, v7
	v_fma_f32 v136, v136, v68, v100
	v_fma_f32 v137, v137, v69, v101
	v_fma_f32 v138, v138, v70, v102
	v_fma_f32 v139, v139, v71, v103
	v_cvt_pk_bf16_f32 v134, v136, v137
	v_cvt_pk_bf16_f32 v135, v138, v139
	global_store_dwordx2 v130, v[134:135], s[14:15] offset:512
	v_mul_f32_e32 v136, v143, v8
	v_mul_f32_e32 v137, v143, v9
	v_mul_f32_e32 v138, v143, v10
	v_mul_f32_e32 v139, v143, v11
	v_fma_f32 v136, v136, v72, v104
	v_fma_f32 v137, v137, v73, v105
	v_fma_f32 v138, v138, v74, v106
	v_fma_f32 v139, v139, v75, v107
	v_cvt_pk_bf16_f32 v132, v136, v137
	v_cvt_pk_bf16_f32 v133, v138, v139
	global_store_dwordx2 v130, v[132:133], s[14:15] offset:1024
	v_mul_f32_e32 v136, v143, v12
	v_mul_f32_e32 v137, v143, v13
	v_mul_f32_e32 v138, v143, v14
	v_mul_f32_e32 v139, v143, v15
	v_fma_f32 v136, v136, v76, v108
	v_fma_f32 v137, v137, v77, v109
	v_fma_f32 v138, v138, v78, v110
	v_fma_f32 v139, v139, v79, v111
	v_cvt_pk_bf16_f32 v134, v136, v137
	v_cvt_pk_bf16_f32 v135, v138, v139
	global_store_dwordx2 v130, v[134:135], s[14:15] offset:1536
	v_mul_f32_e32 v136, v143, v16
	v_mul_f32_e32 v137, v143, v17
	v_mul_f32_e32 v138, v143, v18
	v_mul_f32_e32 v139, v143, v19
	v_fma_f32 v136, v136, v80, v112
	v_fma_f32 v137, v137, v81, v113
	v_fma_f32 v138, v138, v82, v114
	v_fma_f32 v139, v139, v83, v115
	v_cvt_pk_bf16_f32 v132, v136, v137
	v_cvt_pk_bf16_f32 v133, v138, v139
	global_store_dwordx2 v130, v[132:133], s[14:15] offset:2048
	v_mul_f32_e32 v136, v143, v20
	v_mul_f32_e32 v137, v143, v21
	v_mul_f32_e32 v138, v143, v22
	v_mul_f32_e32 v139, v143, v23
	v_fma_f32 v136, v136, v84, v116
	v_fma_f32 v137, v137, v85, v117
	v_fma_f32 v138, v138, v86, v118
	v_fma_f32 v139, v139, v87, v119
	v_cvt_pk_bf16_f32 v134, v136, v137
	v_cvt_pk_bf16_f32 v135, v138, v139
	global_store_dwordx2 v130, v[134:135], s[14:15] offset:2560
	v_mul_f32_e32 v136, v143, v24
	v_mul_f32_e32 v137, v143, v25
	v_mul_f32_e32 v138, v143, v26
	v_mul_f32_e32 v139, v143, v27
	v_fma_f32 v136, v136, v88, v120
	v_fma_f32 v137, v137, v89, v121
	v_fma_f32 v138, v138, v90, v122
	v_fma_f32 v139, v139, v91, v123
	v_cvt_pk_bf16_f32 v132, v136, v137
	v_cvt_pk_bf16_f32 v133, v138, v139
	global_store_dwordx2 v130, v[132:133], s[14:15] offset:3072
	v_mul_f32_e32 v136, v143, v28
	v_mul_f32_e32 v137, v143, v29
	v_mul_f32_e32 v138, v143, v30
	v_mul_f32_e32 v139, v143, v31
	v_fma_f32 v136, v136, v92, v124
	v_fma_f32 v137, v137, v93, v125
	v_fma_f32 v138, v138, v94, v126
	v_fma_f32 v139, v139, v95, v127
	v_cvt_pk_bf16_f32 v134, v136, v137
	v_cvt_pk_bf16_f32 v135, v138, v139
	global_store_dwordx2 v130, v[134:135], s[14:15] offset:3584
	s_add_i32 s4, s6, 2
	s_cmp_lt_u32 s4, 0x4000
	s_cselect_b32 s10, s68, s72
	s_cselect_b32 s11, s69, s73
	s_cselect_b32 s5, 0, 0x4000
	s_sub_i32 s5, s4, s5
	s_lshl_b32 s5, s5, 13
	s_add_u32 s10, s10, s5
	s_addc_u32 s11, s11, 0
	global_load_dwordx4 v[0:3], v128, s[10:11] offset:0 nt
	global_load_dwordx4 v[4:7], v128, s[10:11] offset:1024 nt
	global_load_dwordx4 v[8:11], v128, s[10:11] offset:2048 nt
	global_load_dwordx4 v[12:15], v128, s[10:11] offset:3072 nt
	global_load_dwordx4 v[16:19], v129, s[10:11] offset:0 nt
	global_load_dwordx4 v[20:23], v129, s[10:11] offset:1024 nt
	global_load_dwordx4 v[24:27], v129, s[10:11] offset:2048 nt
	global_load_dwordx4 v[28:31], v129, s[10:11] offset:3072 nt
	s_add_i32 s4, s6, 1
	s_add_i32 s4, s6, 1
	s_lshr_b32 s8, s4, 11
	s_cmp_lt_u32 s4, 0x4000
	s_cselect_b32 s8, s8, 8
	s_cmp_eq_u32 s8, s7
	s_cbranch_scc1 .Lp1_np1
; __device__ __forceinline__ unsigned cvt_pk_bf16(float lo, float hi) { unsigned r; asm volatile("v_cvt_pk_bf16_f32 %0, %1, %2" : "=v"(r) : "v"(lo), "v"(hi)); return r; }
; __device__ __forceinline__ void modulate_store(const f32x4 (&v)[8], float rstd, const float* pn, const float* modr, bf16_t* orow, int lane) {
; #pragma unroll
;     for (int j = 0; j < 8; ++j) { const int col = 4 * lane + 256 * j;
;         const f32x4 g = *(const f32x4*)(pn + col), sh = *(const f32x4*)(modr + col), sc = *(const f32x4*)(modr + DM + col);
;         const f32x4 hh = v[j] * rstd * g * (sc + 1.f) + sh;
;         u32x2 w; w.x = cvt_pk_bf16(hh[0], hh[1]); w.y = cvt_pk_bf16(hh[2], hh[3]);
;         *(u32x2*)(orow + col) = w; }
; }
; __global__ void __launch_bounds__(NWAVES * 64, 2) mk_fwd(Args args) {
;     ...
;         for (int row0 = F.gw * 3; row0 < MT; row0 += F.NGW * 3) {
;             f32x4 v[3][8];
; #pragma unroll
;             for (int q = 0; q < 3; ++q) { const int row = row0 + q; const float* src = row < ML ? x + (size_t)row * DM : ctx + (size_t)(row - ML) * DM; load_row_f32(src, F.lane, v[q]); }
; #pragma unroll
;             for (int q = 0; q < 3; ++q) { const int row = row0 + q; const int r = row < ML ? row / SEQ : 8;
;                 const float rstd = __builtin_amdgcn_rsqf(sumsq8(v[q]) * (1.f / DM) + EPS);
;                 modulate_store(v[q], rstd, pre_norm, mod + (size_t)r * 6144, H + (size_t)row * DM, F.lane); }
;         }
	s_mov_b32 s7, s8
	s_add_i32 s5, s8, 0
	s_mul_i32 s5, s5, 0x6000
	s_add_u32 s24, s84, s5
	s_addc_u32 s25, s85, 0
	s_add_u32 s24, s24, 0x2000
	s_addc_u32 s25, s25, 0
	s_add_i32 s5, s8, 0
	s_mul_i32 s5, s5, 0x6000
	s_add_u32 s16, s84, s5
	s_addc_u32 s17, s85, 0
	s_add_u32 s18, s80, 0x0
	s_addc_u32 s19, s81, 0
	global_load_dwordx4 v[64:67], v128, s[18:19] offset:0
	global_load_dwordx4 v[96:99], v128, s[16:17] offset:0
	global_load_dwordx4 v[68:71], v128, s[18:19] offset:1024
	global_load_dwordx4 v[100:103], v128, s[16:17] offset:1024
	global_load_dwordx4 v[72:75], v128, s[18:19] offset:2048
	global_load_dwordx4 v[104:107], v128, s[16:17] offset:2048
	global_load_dwordx4 v[76:79], v128, s[18:19] offset:3072
	global_load_dwordx4 v[108:111], v128, s[16:17] offset:3072
	global_load_dwordx4 v[80:83], v129, s[18:19] offset:0
	global_load_dwordx4 v[112:115], v129, s[16:17] offset:0
	global_load_dwordx4 v[84:87], v129, s[18:19] offset:1024
	global_load_dwordx4 v[116:119], v129, s[16:17] offset:1024
	global_load_dwordx4 v[88:91], v129, s[18:19] offset:2048
	global_load_dwordx4 v[120:123], v129, s[16:17] offset:2048
	global_load_dwordx4 v[92:95], v129, s[18:19] offset:3072
	global_load_dwordx4 v[124:127], v129, s[16:17] offset:3072
	global_load_dwordx4 v[136:139], v128, s[24:25] offset:0
	s_waitcnt vmcnt(0)
	v_add_f32_e32 v136, 1.0, v136
	v_add_f32_e32 v137, 1.0, v137
	v_add_f32_e32 v138, 1.0, v138
	v_add_f32_e32 v139, 1.0, v139
	v_mul_f32_e32 v64, v64, v136
	v_mul_f32_e32 v65, v65, v137
	v_mul_f32_e32 v66, v66, v138
	v_mul_f32_e32 v67, v67, v139
	global_load_dwordx4 v[136:139], v128, s[24:25] offset:1024
	s_waitcnt vmcnt(0)
	v_add_f32_e32 v136, 1.0, v136
	v_add_f32_e32 v137, 1.0, v137
	v_add_f32_e32 v138, 1.0, v138
	v_add_f32_e32 v139, 1.0, v139
	v_mul_f32_e32 v68, v68, v136
	v_mul_f32_e32 v69, v69, v137
	v_mul_f32_e32 v70, v70, v138
	v_mul_f32_e32 v71, v71, v139
	global_load_dwordx4 v[136:139], v128, s[24:25] offset:2048
	s_waitcnt vmcnt(0)
	v_add_f32_e32 v136, 1.0, v136
	v_add_f32_e32 v137, 1.0, v137
	v_add_f32_e32 v138, 1.0, v138
	v_add_f32_e32 v139, 1.0, v139
	v_mul_f32_e32 v72, v72, v136
	v_mul_f32_e32 v73, v73, v137
	v_mul_f32_e32 v74, v74, v138
	v_mul_f32_e32 v75, v75, v139
	global_load_dwordx4 v[136:139], v128, s[24:25] offset:3072
	s_waitcnt vmcnt(0)
	v_add_f32_e32 v136, 1.0, v136
	v_add_f32_e32 v137, 1.0, v137
	v_add_f32_e32 v138, 1.0, v138
	v_add_f32_e32 v139, 1.0, v139
	v_mul_f32_e32 v76, v76, v136
	v_mul_f32_e32 v77, v77, v137
	v_mul_f32_e32 v78, v78, v138
	v_mul_f32_e32 v79, v79, v139
	global_load_dwordx4 v[136:139], v129, s[24:25] offset:0
	s_waitcnt vmcnt(0)
	v_add_f32_e32 v136, 1.0, v136
	v_add_f32_e32 v137, 1.0, v137
	v_add_f32_e32 v138, 1.0, v138
	v_add_f32_e32 v139, 1.0, v139
	v_mul_f32_e32 v80, v80, v136
	v_mul_f32_e32 v81, v81, v137
	v_mul_f32_e32 v82, v82, v138
	v_mul_f32_e32 v83, v83, v139
	global_load_dwordx4 v[136:139], v129, s[24:25] offset:1024
	s_waitcnt vmcnt(0)
	v_add_f32_e32 v136, 1.0, v136
	v_add_f32_e32 v137, 1.0, v137
	v_add_f32_e32 v138, 1.0, v138
	v_add_f32_e32 v139, 1.0, v139
	v_mul_f32_e32 v84, v84, v136
	v_mul_f32_e32 v85, v85, v137
	v_mul_f32_e32 v86, v86, v138
	v_mul_f32_e32 v87, v87, v139
	global_load_dwordx4 v[136:139], v129, s[24:25] offset:2048
	s_waitcnt vmcnt(0)
	v_add_f32_e32 v136, 1.0, v136
	v_add_f32_e32 v137, 1.0, v137
	v_add_f32_e32 v138, 1.0, v138
	v_add_f32_e32 v139, 1.0, v139
	v_mul_f32_e32 v88, v88, v136
	v_mul_f32_e32 v89, v89, v137
	v_mul_f32_e32 v90, v90, v138
	v_mul_f32_e32 v91, v91, v139
	global_load_dwordx4 v[136:139], v129, s[24:25] offset:3072
	s_waitcnt vmcnt(0)
	v_add_f32_e32 v136, 1.0, v136
	v_add_f32_e32 v137, 1.0, v137
	v_add_f32_e32 v138, 1.0, v138
	v_add_f32_e32 v139, 1.0, v139
	v_mul_f32_e32 v92, v92, v136
	v_mul_f32_e32 v93, v93, v137
	v_mul_f32_e32 v94, v94, v138
	v_mul_f32_e32 v95, v95, v139
.Lp1_np1:
	s_waitcnt vmcnt(16)
	v_mul_f32_e32 v140, v32, v32
	v_mul_f32_e32 v141, v33, v33
	v_fmac_f32_e32 v140, v34, v34
	v_fmac_f32_e32 v141, v35, v35
	v_fmac_f32_e32 v140, v36, v36
	v_fmac_f32_e32 v141, v37, v37
	v_fmac_f32_e32 v140, v38, v38
	v_fmac_f32_e32 v141, v39, v39
	v_fmac_f32_e32 v140, v40, v40
	v_fmac_f32_e32 v141, v41, v41
	v_fmac_f32_e32 v140, v42, v42
	v_fmac_f32_e32 v141, v43, v43
	v_fmac_f32_e32 v140, v44, v44
	v_fmac_f32_e32 v141, v45, v45
	v_fmac_f32_e32 v140, v46, v46
	v_fmac_f32_e32 v141, v47, v47
	v_fmac_f32_e32 v140, v48, v48
	v_fmac_f32_e32 v141, v49, v49
	v_fmac_f32_e32 v140, v50, v50
	v_fmac_f32_e32 v141, v51, v51
	v_fmac_f32_e32 v140, v52, v52
	v_fmac_f32_e32 v141, v53, v53
	v_fmac_f32_e32 v140, v54, v54
	v_fmac_f32_e32 v141, v55, v55
	v_fmac_f32_e32 v140, v56, v56
	v_fmac_f32_e32 v141, v57, v57
	v_fmac_f32_e32 v140, v58, v58
	v_fmac_f32_e32 v141, v59, v59
	v_fmac_f32_e32 v140, v60, v60
	v_fmac_f32_e32 v141, v61, v61
	v_fmac_f32_e32 v140, v62, v62
	v_fmac_f32_e32 v141, v63, v63
	v_add_f32_e32 v140, v140, v141
	s_nop 1
	v_add_f32_dpp v142, v140, v140 quad_perm:[1,0,3,2] row_mask:0xf bank_mask:0xf
	s_nop 1
	v_add_f32_dpp v142, v142, v142 quad_perm:[2,3,0,1] row_mask:0xf bank_mask:0xf
	s_nop 1
	v_add_f32_dpp v142, v142, v142 row_half_mirror row_mask:0xf bank_mask:0xf
	s_nop 1
	v_add_f32_dpp v142, v142, v142 row_mirror row_mask:0xf bank_mask:0xf
	s_nop 1
	v_readlane_b32 s20, v142, 0
	v_readlane_b32 s21, v142, 16
	v_readlane_b32 s22, v142, 32
	v_readlane_b32 s23, v142, 48
	s_nop 1
	v_mov_b32_e32 v143, s20
	v_add_f32_e32 v143, s21, v143
	v_add_f32_e32 v143, s22, v143
	v_add_f32_e32 v143, s23, v143
	v_fmamk_f32 v143, v143, 0x3a000000, v131
	v_rsq_f32_e32 v143, v143
	s_nop 0
	s_add_i32 s4, s6, 1
	s_lshl_b32 s5, s4, 12
	s_add_u32 s14, s84, s5
	s_addc_u32 s15, s85, 0
; __device__ __forceinline__ unsigned cvt_pk_bf16(float lo, float hi) { unsigned r; asm volatile("v_cvt_pk_bf16_f32 %0, %1, %2" : "=v"(r) : "v"(lo), "v"(hi)); return r; }
; __device__ __forceinline__ void modulate_store(const f32x4 (&v)[8], float rstd, const float* pn, const float* modr, bf16_t* orow, int lane) {
; #pragma unroll
;     for (int j = 0; j < 8; ++j) { const int col = 4 * lane + 256 * j;
;         const f32x4 g = *(const f32x4*)(pn + col), sh = *(const f32x4*)(modr + col), sc = *(const f32x4*)(modr + DM + col);
;         const f32x4 hh = v[j] * rstd * g * (sc + 1.f) + sh;
;         u32x2 w; w.x = cvt_pk_bf16(hh[0], hh[1]); w.y = cvt_pk_bf16(hh[2], hh[3]);
;         *(u32x2*)(orow + col) = w; }
; }
; __global__ void __launch_bounds__(NWAVES * 64, 2) mk_fwd(Args args) {
;     ...
;         for (int row0 = F.gw * 3; row0 < MT; row0 += F.NGW * 3) {
;             f32x4 v[3][8];
; #pragma unroll
;             for (int q = 0; q < 3; ++q) { const int row = row0 + q; const float* src = row < ML ? x + (size_t)row * DM : ctx + (size_t)(row - ML) * DM; load_row_f32(src, F.lane, v[q]); }
; #pragma unroll
;             for (int q = 0; q < 3; ++q) { const int row = row0 + q; const int r = row < ML ? row / SEQ : 8;
;                 const float rstd = __builtin_amdgcn_rsqf(sumsq8(v[q]) * (1.f / DM) + EPS);
;                 modulate_store(v[q], rstd, pre_norm, mod + (size_t)r * 6144, H + (size_t)row * DM, F.lane); }
;         }
	s_add_u32 s14, s14, 0x1a800000
	s_addc_u32 s15, s15, 0
	v_mul_f32_e32 v136, v143, v32
	v_mul_f32_e32 v137, v143, v33
	v_mul_f32_e32 v138, v143, v34
	v_mul_f32_e32 v139, v143, v35
	v_fma_f32 v136, v136, v64, v96
	v_fma_f32 v137, v137, v65, v97
	v_fma_f32 v138, v138, v66, v98
	v_fma_f32 v139, v139, v67, v99
	v_cvt_pk_bf16_f32 v132, v136, v137
	v_cvt_pk_bf16_f32 v133, v138, v139
	global_store_dwordx2 v130, v[132:133], s[14:15] offset:0
	v_mul_f32_e32 v136, v143, v36
	v_mul_f32_e32 v137, v143, v37
	v_mul_f32_e32 v138, v143, v38
	v_mul_f32_e32 v139, v143, v39
	v_fma_f32 v136, v136, v68, v100
	v_fma_f32 v137, v137, v69, v101
	v_fma_f32 v138, v138, v70, v102
	v_fma_f32 v139, v139, v71, v103
	v_cvt_pk_bf16_f32 v134, v136, v137
	v_cvt_pk_bf16_f32 v135, v138, v139
	global_store_dwordx2 v130, v[134:135], s[14:15] offset:512
	v_mul_f32_e32 v136, v143, v40
	v_mul_f32_e32 v137, v143, v41
	v_mul_f32_e32 v138, v143, v42
	v_mul_f32_e32 v139, v143, v43
	v_fma_f32 v136, v136, v72, v104
	v_fma_f32 v137, v137, v73, v105
	v_fma_f32 v138, v138, v74, v106
	v_fma_f32 v139, v139, v75, v107
	v_cvt_pk_bf16_f32 v132, v136, v137
	v_cvt_pk_bf16_f32 v133, v138, v139
	global_store_dwordx2 v130, v[132:133], s[14:15] offset:1024
	v_mul_f32_e32 v136, v143, v44
	v_mul_f32_e32 v137, v143, v45
	v_mul_f32_e32 v138, v143, v46
	v_mul_f32_e32 v139, v143, v47
	v_fma_f32 v136, v136, v76, v108
	v_fma_f32 v137, v137, v77, v109
	v_fma_f32 v138, v138, v78, v110
	v_fma_f32 v139, v139, v79, v111
	v_cvt_pk_bf16_f32 v134, v136, v137
	v_cvt_pk_bf16_f32 v135, v138, v139
	global_store_dwordx2 v130, v[134:135], s[14:15] offset:1536
	v_mul_f32_e32 v136, v143, v48
	v_mul_f32_e32 v137, v143, v49
	v_mul_f32_e32 v138, v143, v50
	v_mul_f32_e32 v139, v143, v51
	v_fma_f32 v136, v136, v80, v112
	v_fma_f32 v137, v137, v81, v113
	v_fma_f32 v138, v138, v82, v114
	v_fma_f32 v139, v139, v83, v115
	v_cvt_pk_bf16_f32 v132, v136, v137
	v_cvt_pk_bf16_f32 v133, v138, v139
	global_store_dwordx2 v130, v[132:133], s[14:15] offset:2048
	v_mul_f32_e32 v136, v143, v52
	v_mul_f32_e32 v137, v143, v53
	v_mul_f32_e32 v138, v143, v54
	v_mul_f32_e32 v139, v143, v55
	v_fma_f32 v136, v136, v84, v116
	v_fma_f32 v137, v137, v85, v117
	v_fma_f32 v138, v138, v86, v118
	v_fma_f32 v139, v139, v87, v119
	v_cvt_pk_bf16_f32 v134, v136, v137
	v_cvt_pk_bf16_f32 v135, v138, v139
	global_store_dwordx2 v130, v[134:135], s[14:15] offset:2560
	v_mul_f32_e32 v136, v143, v56
	v_mul_f32_e32 v137, v143, v57
	v_mul_f32_e32 v138, v143, v58
	v_mul_f32_e32 v139, v143, v59
	v_fma_f32 v136, v136, v88, v120
	v_fma_f32 v137, v137, v89, v121
	v_fma_f32 v138, v138, v90, v122
	v_fma_f32 v139, v139, v91, v123
	v_cvt_pk_bf16_f32 v132, v136, v137
	v_cvt_pk_bf16_f32 v133, v138, v139
	global_store_dwordx2 v130, v[132:133], s[14:15] offset:3072
	v_mul_f32_e32 v136, v143, v60
	v_mul_f32_e32 v137, v143, v61
	v_mul_f32_e32 v138, v143, v62
	v_mul_f32_e32 v139, v143, v63
	v_fma_f32 v136, v136, v92, v124
	v_fma_f32 v137, v137, v93, v125
	v_fma_f32 v138, v138, v94, v126
	v_fma_f32 v139, v139, v95, v127
	v_cvt_pk_bf16_f32 v134, v136, v137
	v_cvt_pk_bf16_f32 v135, v138, v139
	global_store_dwordx2 v130, v[134:135], s[14:15] offset:3584
	s_add_i32 s4, s6, 3
	s_cmp_lt_u32 s4, 0x4000
	s_cselect_b32 s10, s68, s72
	s_cselect_b32 s11, s69, s73
	s_cselect_b32 s5, 0, 0x4000
	s_sub_i32 s5, s4, s5
	s_lshl_b32 s5, s5, 13
	s_add_u32 s10, s10, s5
	s_addc_u32 s11, s11, 0
	global_load_dwordx4 v[32:35], v128, s[10:11] offset:0 nt
	global_load_dwordx4 v[36:39], v128, s[10:11] offset:1024 nt
	global_load_dwordx4 v[40:43], v128, s[10:11] offset:2048 nt
	global_load_dwordx4 v[44:47], v128, s[10:11] offset:3072 nt
	global_load_dwordx4 v[48:51], v129, s[10:11] offset:0 nt
	global_load_dwordx4 v[52:55], v129, s[10:11] offset:1024 nt
	global_load_dwordx4 v[56:59], v129, s[10:11] offset:2048 nt
	global_load_dwordx4 v[60:63], v129, s[10:11] offset:3072 nt
	s_add_i32 s4, s6, 2
	s_add_i32 s4, s6, 2
	s_lshr_b32 s8, s4, 11
	s_cmp_lt_u32 s4, 0x4000
	s_cselect_b32 s8, s8, 8
	s_cmp_eq_u32 s8, s7
	s_cbranch_scc1 .Lp1_np2
	s_mov_b32 s7, s8
	s_add_i32 s5, s8, 0
	s_mul_i32 s5, s5, 0x6000
	s_add_u32 s24, s84, s5
	s_addc_u32 s25, s85, 0
	s_add_u32 s24, s24, 0x2000
	s_addc_u32 s25, s25, 0
	s_add_i32 s5, s8, 0
	s_mul_i32 s5, s5, 0x6000
	s_add_u32 s16, s84, s5
	s_addc_u32 s17, s85, 0
	s_add_u32 s18, s80, 0x0
	s_addc_u32 s19, s81, 0
	global_load_dwordx4 v[64:67], v128, s[18:19] offset:0
	global_load_dwordx4 v[96:99], v128, s[16:17] offset:0
	global_load_dwordx4 v[68:71], v128, s[18:19] offset:1024
	global_load_dwordx4 v[100:103], v128, s[16:17] offset:1024
	global_load_dwordx4 v[72:75], v128, s[18:19] offset:2048
	global_load_dwordx4 v[104:107], v128, s[16:17] offset:2048
	global_load_dwordx4 v[76:79], v128, s[18:19] offset:3072
	global_load_dwordx4 v[108:111], v128, s[16:17] offset:3072
	global_load_dwordx4 v[80:83], v129, s[18:19] offset:0
	global_load_dwordx4 v[112:115], v129, s[16:17] offset:0
	global_load_dwordx4 v[84:87], v129, s[18:19] offset:1024
	global_load_dwordx4 v[116:119], v129, s[16:17] offset:1024
	global_load_dwordx4 v[88:91], v129, s[18:19] offset:2048
	global_load_dwordx4 v[120:123], v129, s[16:17] offset:2048
	global_load_dwordx4 v[92:95], v129, s[18:19] offset:3072
	global_load_dwordx4 v[124:127], v129, s[16:17] offset:3072
	global_load_dwordx4 v[136:139], v128, s[24:25] offset:0
	s_waitcnt vmcnt(0)
	v_add_f32_e32 v136, 1.0, v136
	v_add_f32_e32 v137, 1.0, v137
	v_add_f32_e32 v138, 1.0, v138
	v_add_f32_e32 v139, 1.0, v139
	v_mul_f32_e32 v64, v64, v136
	v_mul_f32_e32 v65, v65, v137
	v_mul_f32_e32 v66, v66, v138
	v_mul_f32_e32 v67, v67, v139
	global_load_dwordx4 v[136:139], v128, s[24:25] offset:1024
	s_waitcnt vmcnt(0)
; __device__ __forceinline__ unsigned cvt_pk_bf16(float lo, float hi) { unsigned r; asm volatile("v_cvt_pk_bf16_f32 %0, %1, %2" : "=v"(r) : "v"(lo), "v"(hi)); return r; }
; __device__ __forceinline__ void modulate_store(const f32x4 (&v)[8], float rstd, const float* pn, const float* modr, bf16_t* orow, int lane) {
; #pragma unroll
;     for (int j = 0; j < 8; ++j) { const int col = 4 * lane + 256 * j;
;         const f32x4 g = *(const f32x4*)(pn + col), sh = *(const f32x4*)(modr + col), sc = *(const f32x4*)(modr + DM + col);
;         const f32x4 hh = v[j] * rstd * g * (sc + 1.f) + sh;
;         u32x2 w; w.x = cvt_pk_bf16(hh[0], hh[1]); w.y = cvt_pk_bf16(hh[2], hh[3]);
;         *(u32x2*)(orow + col) = w; }
; }
; __global__ void __launch_bounds__(NWAVES * 64, 2) mk_fwd(Args args) {
;     ...
;         for (int row0 = F.gw * 3; row0 < MT; row0 += F.NGW * 3) {
;             f32x4 v[3][8];
; #pragma unroll
;             for (int q = 0; q < 3; ++q) { const int row = row0 + q; const float* src = row < ML ? x + (size_t)row * DM : ctx + (size_t)(row - ML) * DM; load_row_f32(src, F.lane, v[q]); }
; #pragma unroll
;             for (int q = 0; q < 3; ++q) { const int row = row0 + q; const int r = row < ML ? row / SEQ : 8;
;                 const float rstd = __builtin_amdgcn_rsqf(sumsq8(v[q]) * (1.f / DM) + EPS);
;                 modulate_store(v[q], rstd, pre_norm, mod + (size_t)r * 6144, H + (size_t)row * DM, F.lane); }
;         }
	v_add_f32_e32 v136, 1.0, v136
	v_add_f32_e32 v137, 1.0, v137
	v_add_f32_e32 v138, 1.0, v138
	v_add_f32_e32 v139, 1.0, v139
	v_mul_f32_e32 v68, v68, v136
	v_mul_f32_e32 v69, v69, v137
	v_mul_f32_e32 v70, v70, v138
	v_mul_f32_e32 v71, v71, v139
	global_load_dwordx4 v[136:139], v128, s[24:25] offset:2048
	s_waitcnt vmcnt(0)
	v_add_f32_e32 v136, 1.0, v136
	v_add_f32_e32 v137, 1.0, v137
	v_add_f32_e32 v138, 1.0, v138
	v_add_f32_e32 v139, 1.0, v139
	v_mul_f32_e32 v72, v72, v136
	v_mul_f32_e32 v73, v73, v137
	v_mul_f32_e32 v74, v74, v138
	v_mul_f32_e32 v75, v75, v139
	global_load_dwordx4 v[136:139], v128, s[24:25] offset:3072
	s_waitcnt vmcnt(0)
	v_add_f32_e32 v136, 1.0, v136
	v_add_f32_e32 v137, 1.0, v137
	v_add_f32_e32 v138, 1.0, v138
	v_add_f32_e32 v139, 1.0, v139
	v_mul_f32_e32 v76, v76, v136
	v_mul_f32_e32 v77, v77, v137
	v_mul_f32_e32 v78, v78, v138
	v_mul_f32_e32 v79, v79, v139
	global_load_dwordx4 v[136:139], v129, s[24:25] offset:0
	s_waitcnt vmcnt(0)
	v_add_f32_e32 v136, 1.0, v136
	v_add_f32_e32 v137, 1.0, v137
	v_add_f32_e32 v138, 1.0, v138
	v_add_f32_e32 v139, 1.0, v139
	v_mul_f32_e32 v80, v80, v136
	v_mul_f32_e32 v81, v81, v137
	v_mul_f32_e32 v82, v82, v138
	v_mul_f32_e32 v83, v83, v139
	global_load_dwordx4 v[136:139], v129, s[24:25] offset:1024
	s_waitcnt vmcnt(0)
	v_add_f32_e32 v136, 1.0, v136
	v_add_f32_e32 v137, 1.0, v137
	v_add_f32_e32 v138, 1.0, v138
	v_add_f32_e32 v139, 1.0, v139
	v_mul_f32_e32 v84, v84, v136
	v_mul_f32_e32 v85, v85, v137
	v_mul_f32_e32 v86, v86, v138
	v_mul_f32_e32 v87, v87, v139
	global_load_dwordx4 v[136:139], v129, s[24:25] offset:2048
	s_waitcnt vmcnt(0)
	v_add_f32_e32 v136, 1.0, v136
	v_add_f32_e32 v137, 1.0, v137
	v_add_f32_e32 v138, 1.0, v138
	v_add_f32_e32 v139, 1.0, v139
	v_mul_f32_e32 v88, v88, v136
	v_mul_f32_e32 v89, v89, v137
	v_mul_f32_e32 v90, v90, v138
	v_mul_f32_e32 v91, v91, v139
	global_load_dwordx4 v[136:139], v129, s[24:25] offset:3072
	s_waitcnt vmcnt(0)
	v_add_f32_e32 v136, 1.0, v136
	v_add_f32_e32 v137, 1.0, v137
	v_add_f32_e32 v138, 1.0, v138
	v_add_f32_e32 v139, 1.0, v139
	v_mul_f32_e32 v92, v92, v136
	v_mul_f32_e32 v93, v93, v137
	v_mul_f32_e32 v94, v94, v138
	v_mul_f32_e32 v95, v95, v139
.Lp1_np2:
	s_waitcnt vmcnt(16)
	v_mul_f32_e32 v140, v0, v0
	v_mul_f32_e32 v141, v1, v1
	v_fmac_f32_e32 v140, v2, v2
	v_fmac_f32_e32 v141, v3, v3
	v_fmac_f32_e32 v140, v4, v4
	v_fmac_f32_e32 v141, v5, v5
	v_fmac_f32_e32 v140, v6, v6
	v_fmac_f32_e32 v141, v7, v7
	v_fmac_f32_e32 v140, v8, v8
	v_fmac_f32_e32 v141, v9, v9
	v_fmac_f32_e32 v140, v10, v10
	v_fmac_f32_e32 v141, v11, v11
	v_fmac_f32_e32 v140, v12, v12
	v_fmac_f32_e32 v141, v13, v13
	v_fmac_f32_e32 v140, v14, v14
	v_fmac_f32_e32 v141, v15, v15
	v_fmac_f32_e32 v140, v16, v16
	v_fmac_f32_e32 v141, v17, v17
	v_fmac_f32_e32 v140, v18, v18
	v_fmac_f32_e32 v141, v19, v19
	v_fmac_f32_e32 v140, v20, v20
	v_fmac_f32_e32 v141, v21, v21
	v_fmac_f32_e32 v140, v22, v22
	v_fmac_f32_e32 v141, v23, v23
	v_fmac_f32_e32 v140, v24, v24
	v_fmac_f32_e32 v141, v25, v25
	v_fmac_f32_e32 v140, v26, v26
	v_fmac_f32_e32 v141, v27, v27
	v_fmac_f32_e32 v140, v28, v28
	v_fmac_f32_e32 v141, v29, v29
	v_fmac_f32_e32 v140, v30, v30
	v_fmac_f32_e32 v141, v31, v31
	v_add_f32_e32 v140, v140, v141
	s_nop 1
	v_add_f32_dpp v142, v140, v140 quad_perm:[1,0,3,2] row_mask:0xf bank_mask:0xf
	s_nop 1
	v_add_f32_dpp v142, v142, v142 quad_perm:[2,3,0,1] row_mask:0xf bank_mask:0xf
	s_nop 1
	v_add_f32_dpp v142, v142, v142 row_half_mirror row_mask:0xf bank_mask:0xf
	s_nop 1
	v_add_f32_dpp v142, v142, v142 row_mirror row_mask:0xf bank_mask:0xf
	s_nop 1
	v_readlane_b32 s20, v142, 0
	v_readlane_b32 s21, v142, 16
	v_readlane_b32 s22, v142, 32
	v_readlane_b32 s23, v142, 48
	s_nop 1
	v_mov_b32_e32 v143, s20
	v_add_f32_e32 v143, s21, v143
	v_add_f32_e32 v143, s22, v143
	v_add_f32_e32 v143, s23, v143
	v_fmamk_f32 v143, v143, 0x3a000000, v131
	v_rsq_f32_e32 v143, v143
	s_nop 0
	s_add_i32 s4, s6, 2
	s_lshl_b32 s5, s4, 12
	s_add_u32 s14, s84, s5
	s_addc_u32 s15, s85, 0
	s_add_u32 s14, s14, 0x1a800000
	s_addc_u32 s15, s15, 0
	v_mul_f32_e32 v136, v143, v0
	v_mul_f32_e32 v137, v143, v1
	v_mul_f32_e32 v138, v143, v2
	v_mul_f32_e32 v139, v143, v3
	v_fma_f32 v136, v136, v64, v96
	v_fma_f32 v137, v137, v65, v97
	v_fma_f32 v138, v138, v66, v98
	v_fma_f32 v139, v139, v67, v99
	v_cvt_pk_bf16_f32 v132, v136, v137
	v_cvt_pk_bf16_f32 v133, v138, v139
	global_store_dwordx2 v130, v[132:133], s[14:15] offset:0
	v_mul_f32_e32 v136, v143, v4
	v_mul_f32_e32 v137, v143, v5
	v_mul_f32_e32 v138, v143, v6
	v_mul_f32_e32 v139, v143, v7
	v_fma_f32 v136, v136, v68, v100
	v_fma_f32 v137, v137, v69, v101
	v_fma_f32 v138, v138, v70, v102
	v_fma_f32 v139, v139, v71, v103
	v_cvt_pk_bf16_f32 v134, v136, v137
	v_cvt_pk_bf16_f32 v135, v138, v139
	global_store_dwordx2 v130, v[134:135], s[14:15] offset:512
	v_mul_f32_e32 v136, v143, v8
	v_mul_f32_e32 v137, v143, v9
	v_mul_f32_e32 v138, v143, v10
	v_mul_f32_e32 v139, v143, v11
	v_fma_f32 v136, v136, v72, v104
	v_fma_f32 v137, v137, v73, v105
	v_fma_f32 v138, v138, v74, v106
	v_fma_f32 v139, v139, v75, v107
	v_cvt_pk_bf16_f32 v132, v136, v137
	v_cvt_pk_bf16_f32 v133, v138, v139
	global_store_dwordx2 v130, v[132:133], s[14:15] offset:1024
	v_mul_f32_e32 v136, v143, v12
	v_mul_f32_e32 v137, v143, v13
	v_mul_f32_e32 v138, v143, v14
	v_mul_f32_e32 v139, v143, v15
	v_fma_f32 v136, v136, v76, v108
	v_fma_f32 v137, v137, v77, v109
	v_fma_f32 v138, v138, v78, v110
	v_fma_f32 v139, v139, v79, v111
	v_cvt_pk_bf16_f32 v134, v136, v137
	v_cvt_pk_bf16_f32 v135, v138, v139
	global_store_dwordx2 v130, v[134:135], s[14:15] offset:1536
	v_mul_f32_e32 v136, v143, v16
	v_mul_f32_e32 v137, v143, v17
; __device__ __forceinline__ unsigned cvt_pk_bf16(float lo, float hi) { unsigned r; asm volatile("v_cvt_pk_bf16_f32 %0, %1, %2" : "=v"(r) : "v"(lo), "v"(hi)); return r; }
; __device__ __forceinline__ void modulate_store(const f32x4 (&v)[8], float rstd, const float* pn, const float* modr, bf16_t* orow, int lane) {
; #pragma unroll
;     for (int j = 0; j < 8; ++j) { const int col = 4 * lane + 256 * j;
;         const f32x4 g = *(const f32x4*)(pn + col), sh = *(const f32x4*)(modr + col), sc = *(const f32x4*)(modr + DM + col);
;         const f32x4 hh = v[j] * rstd * g * (sc + 1.f) + sh;
;         u32x2 w; w.x = cvt_pk_bf16(hh[0], hh[1]); w.y = cvt_pk_bf16(hh[2], hh[3]);
;         *(u32x2*)(orow + col) = w; }
; }
; __global__ void __launch_bounds__(NWAVES * 64, 2) mk_fwd(Args args) {
;     ...
;         for (int row0 = F.gw * 3; row0 < MT; row0 += F.NGW * 3) {
;             f32x4 v[3][8];
; #pragma unroll
;             for (int q = 0; q < 3; ++q) { const int row = row0 + q; const float* src = row < ML ? x + (size_t)row * DM : ctx + (size_t)(row - ML) * DM; load_row_f32(src, F.lane, v[q]); }
; #pragma unroll
;             for (int q = 0; q < 3; ++q) { const int row = row0 + q; const int r = row < ML ? row / SEQ : 8;
;                 const float rstd = __builtin_amdgcn_rsqf(sumsq8(v[q]) * (1.f / DM) + EPS);
;                 modulate_store(v[q], rstd, pre_norm, mod + (size_t)r * 6144, H + (size_t)row * DM, F.lane); }
;         }
	v_mul_f32_e32 v138, v143, v18
	v_mul_f32_e32 v139, v143, v19
	v_fma_f32 v136, v136, v80, v112
	v_fma_f32 v137, v137, v81, v113
	v_fma_f32 v138, v138, v82, v114
	v_fma_f32 v139, v139, v83, v115
	v_cvt_pk_bf16_f32 v132, v136, v137
	v_cvt_pk_bf16_f32 v133, v138, v139
	global_store_dwordx2 v130, v[132:133], s[14:15] offset:2048
	v_mul_f32_e32 v136, v143, v20
	v_mul_f32_e32 v137, v143, v21
	v_mul_f32_e32 v138, v143, v22
	v_mul_f32_e32 v139, v143, v23
	v_fma_f32 v136, v136, v84, v116
	v_fma_f32 v137, v137, v85, v117
	v_fma_f32 v138, v138, v86, v118
	v_fma_f32 v139, v139, v87, v119
	v_cvt_pk_bf16_f32 v134, v136, v137
	v_cvt_pk_bf16_f32 v135, v138, v139
	global_store_dwordx2 v130, v[134:135], s[14:15] offset:2560
	v_mul_f32_e32 v136, v143, v24
	v_mul_f32_e32 v137, v143, v25
	v_mul_f32_e32 v138, v143, v26
	v_mul_f32_e32 v139, v143, v27
	v_fma_f32 v136, v136, v88, v120
	v_fma_f32 v137, v137, v89, v121
	v_fma_f32 v138, v138, v90, v122
	v_fma_f32 v139, v139, v91, v123
	v_cvt_pk_bf16_f32 v132, v136, v137
	v_cvt_pk_bf16_f32 v133, v138, v139
	global_store_dwordx2 v130, v[132:133], s[14:15] offset:3072
	v_mul_f32_e32 v136, v143, v28
	v_mul_f32_e32 v137, v143, v29
	v_mul_f32_e32 v138, v143, v30
	v_mul_f32_e32 v139, v143, v31
	v_fma_f32 v136, v136, v92, v124
	v_fma_f32 v137, v137, v93, v125
	v_fma_f32 v138, v138, v94, v126
	v_fma_f32 v139, v139, v95, v127
	v_cvt_pk_bf16_f32 v134, v136, v137
	v_cvt_pk_bf16_f32 v135, v138, v139
	global_store_dwordx2 v130, v[134:135], s[14:15] offset:3584
	s_add_i32 s4, s6, 4
	s_cmp_lt_u32 s4, 0x4000
	s_cselect_b32 s10, s68, s72
	s_cselect_b32 s11, s69, s73
	s_cselect_b32 s5, 0, 0x4000
	s_sub_i32 s5, s4, s5
	s_lshl_b32 s5, s5, 13
	s_add_u32 s10, s10, s5
	s_addc_u32 s11, s11, 0
	global_load_dwordx4 v[0:3], v128, s[10:11] offset:0 nt
	global_load_dwordx4 v[4:7], v128, s[10:11] offset:1024 nt
	global_load_dwordx4 v[8:11], v128, s[10:11] offset:2048 nt
	global_load_dwordx4 v[12:15], v128, s[10:11] offset:3072 nt
	global_load_dwordx4 v[16:19], v129, s[10:11] offset:0 nt
	global_load_dwordx4 v[20:23], v129, s[10:11] offset:1024 nt
	global_load_dwordx4 v[24:27], v129, s[10:11] offset:2048 nt
	global_load_dwordx4 v[28:31], v129, s[10:11] offset:3072 nt
	s_add_i32 s4, s6, 3
	s_add_i32 s4, s6, 3
	s_lshr_b32 s8, s4, 11
	s_cmp_lt_u32 s4, 0x4000
	s_cselect_b32 s8, s8, 8
	s_cmp_eq_u32 s8, s7
	s_cbranch_scc1 .Lp1_np3
	s_mov_b32 s7, s8
	s_add_i32 s5, s8, 0
	s_mul_i32 s5, s5, 0x6000
	s_add_u32 s24, s84, s5
	s_addc_u32 s25, s85, 0
	s_add_u32 s24, s24, 0x2000
	s_addc_u32 s25, s25, 0
	s_add_i32 s5, s8, 0
	s_mul_i32 s5, s5, 0x6000
	s_add_u32 s16, s84, s5
	s_addc_u32 s17, s85, 0
	s_add_u32 s18, s80, 0x0
	s_addc_u32 s19, s81, 0
	global_load_dwordx4 v[64:67], v128, s[18:19] offset:0
	global_load_dwordx4 v[96:99], v128, s[16:17] offset:0
	global_load_dwordx4 v[68:71], v128, s[18:19] offset:1024
	global_load_dwordx4 v[100:103], v128, s[16:17] offset:1024
	global_load_dwordx4 v[72:75], v128, s[18:19] offset:2048
	global_load_dwordx4 v[104:107], v128, s[16:17] offset:2048
	global_load_dwordx4 v[76:79], v128, s[18:19] offset:3072
	global_load_dwordx4 v[108:111], v128, s[16:17] offset:3072
	global_load_dwordx4 v[80:83], v129, s[18:19] offset:0
	global_load_dwordx4 v[112:115], v129, s[16:17] offset:0
	global_load_dwordx4 v[84:87], v129, s[18:19] offset:1024
	global_load_dwordx4 v[116:119], v129, s[16:17] offset:1024
	global_load_dwordx4 v[88:91], v129, s[18:19] offset:2048
	global_load_dwordx4 v[120:123], v129, s[16:17] offset:2048
	global_load_dwordx4 v[92:95], v129, s[18:19] offset:3072
	global_load_dwordx4 v[124:127], v129, s[16:17] offset:3072
	global_load_dwordx4 v[136:139], v128, s[24:25] offset:0
	s_waitcnt vmcnt(0)
	v_add_f32_e32 v136, 1.0, v136
	v_add_f32_e32 v137, 1.0, v137
	v_add_f32_e32 v138, 1.0, v138
	v_add_f32_e32 v139, 1.0, v139
	v_mul_f32_e32 v64, v64, v136
	v_mul_f32_e32 v65, v65, v137
	v_mul_f32_e32 v66, v66, v138
	v_mul_f32_e32 v67, v67, v139
	global_load_dwordx4 v[136:139], v128, s[24:25] offset:1024
	s_waitcnt vmcnt(0)
	v_add_f32_e32 v136, 1.0, v136
	v_add_f32_e32 v137, 1.0, v137
	v_add_f32_e32 v138, 1.0, v138
	v_add_f32_e32 v139, 1.0, v139
	v_mul_f32_e32 v68, v68, v136
	v_mul_f32_e32 v69, v69, v137
	v_mul_f32_e32 v70, v70, v138
	v_mul_f32_e32 v71, v71, v139
	global_load_dwordx4 v[136:139], v128, s[24:25] offset:2048
	s_waitcnt vmcnt(0)
	v_add_f32_e32 v136, 1.0, v136
	v_add_f32_e32 v137, 1.0, v137
	v_add_f32_e32 v138, 1.0, v138
	v_add_f32_e32 v139, 1.0, v139
	v_mul_f32_e32 v72, v72, v136
	v_mul_f32_e32 v73, v73, v137
	v_mul_f32_e32 v74, v74, v138
	v_mul_f32_e32 v75, v75, v139
	global_load_dwordx4 v[136:139], v128, s[24:25] offset:3072
	s_waitcnt vmcnt(0)
	v_add_f32_e32 v136, 1.0, v136
	v_add_f32_e32 v137, 1.0, v137
	v_add_f32_e32 v138, 1.0, v138
	v_add_f32_e32 v139, 1.0, v139
	v_mul_f32_e32 v76, v76, v136
	v_mul_f32_e32 v77, v77, v137
	v_mul_f32_e32 v78, v78, v138
	v_mul_f32_e32 v79, v79, v139
	global_load_dwordx4 v[136:139], v129, s[24:25] offset:0
	s_waitcnt vmcnt(0)
	v_add_f32_e32 v136, 1.0, v136
	v_add_f32_e32 v137, 1.0, v137
	v_add_f32_e32 v138, 1.0, v138
	v_add_f32_e32 v139, 1.0, v139
	v_mul_f32_e32 v80, v80, v136
	v_mul_f32_e32 v81, v81, v137
	v_mul_f32_e32 v82, v82, v138
	v_mul_f32_e32 v83, v83, v139
	global_load_dwordx4 v[136:139], v129, s[24:25] offset:1024
	s_waitcnt vmcnt(0)
	v_add_f32_e32 v136, 1.0, v136
	v_add_f32_e32 v137, 1.0, v137
	v_add_f32_e32 v138, 1.0, v138
	v_add_f32_e32 v139, 1.0, v139
	v_mul_f32_e32 v84, v84, v136
	v_mul_f32_e32 v85, v85, v137
	v_mul_f32_e32 v86, v86, v138
	v_mul_f32_e32 v87, v87, v139
	global_load_dwordx4 v[136:139], v129, s[24:25] offset:2048
	s_waitcnt vmcnt(0)
	v_add_f32_e32 v136, 1.0, v136
	v_add_f32_e32 v137, 1.0, v137
	v_add_f32_e32 v138, 1.0, v138
	v_add_f32_e32 v139, 1.0, v139
	v_mul_f32_e32 v88, v88, v136
	v_mul_f32_e32 v89, v89, v137
	v_mul_f32_e32 v90, v90, v138
	v_mul_f32_e32 v91, v91, v139
	global_load_dwordx4 v[136:139], v129, s[24:25] offset:3072
	s_waitcnt vmcnt(0)
	v_add_f32_e32 v136, 1.0, v136
	v_add_f32_e32 v137, 1.0, v137
	v_add_f32_e32 v138, 1.0, v138
	v_add_f32_e32 v139, 1.0, v139
	v_mul_f32_e32 v92, v92, v136
	v_mul_f32_e32 v93, v93, v137
	v_mul_f32_e32 v94, v94, v138
	v_mul_f32_e32 v95, v95, v139
; __device__ __forceinline__ unsigned cvt_pk_bf16(float lo, float hi) { unsigned r; asm volatile("v_cvt_pk_bf16_f32 %0, %1, %2" : "=v"(r) : "v"(lo), "v"(hi)); return r; }
; __device__ __forceinline__ float sumsq8(const f32x4 (&v)[8]) {
;     float s = 0.f;
; #pragma unroll
;     for (int j = 0; j < 8; ++j) s += (v[j][0] * v[j][0] + v[j][1] * v[j][1]) + (v[j][2] * v[j][2] + v[j][3] * v[j][3]);
;     return wave_sum(s);
; }
; __device__ __forceinline__ void modulate_store(const f32x4 (&v)[8], float rstd, const float* pn, const float* modr, bf16_t* orow, int lane) {
; #pragma unroll
;     for (int j = 0; j < 8; ++j) { const int col = 4 * lane + 256 * j;
;         const f32x4 g = *(const f32x4*)(pn + col), sh = *(const f32x4*)(modr + col), sc = *(const f32x4*)(modr + DM + col);
;         const f32x4 hh = v[j] * rstd * g * (sc + 1.f) + sh;
;         u32x2 w; w.x = cvt_pk_bf16(hh[0], hh[1]); w.y = cvt_pk_bf16(hh[2], hh[3]);
;         *(u32x2*)(orow + col) = w; }
; __global__ void __launch_bounds__(NWAVES * 64, 2) mk_fwd(Args args) {
;     ...
;         for (int row0 = F.gw * 3; row0 < MT; row0 += F.NGW * 3) {
;             f32x4 v[3][8];
; #pragma unroll
;             for (int q = 0; q < 3; ++q) { const int row = row0 + q; const float* src = row < ML ? x + (size_t)row * DM : ctx + (size_t)(row - ML) * DM; load_row_f32(src, F.lane, v[q]); }
; #pragma unroll
;             for (int q = 0; q < 3; ++q) { const int row = row0 + q; const int r = row < ML ? row / SEQ : 8;
;                 const float rstd = __builtin_amdgcn_rsqf(sumsq8(v[q]) * (1.f / DM) + EPS);
;                 modulate_store(v[q], rstd, pre_norm, mod + (size_t)r * 6144, H + (size_t)row * DM, F.lane); }
.Lp1_np3:
	s_waitcnt vmcnt(16)
	v_mul_f32_e32 v140, v32, v32
	v_mul_f32_e32 v141, v33, v33
	v_fmac_f32_e32 v140, v34, v34
	v_fmac_f32_e32 v141, v35, v35
	v_fmac_f32_e32 v140, v36, v36
	v_fmac_f32_e32 v141, v37, v37
	v_fmac_f32_e32 v140, v38, v38
	v_fmac_f32_e32 v141, v39, v39
	v_fmac_f32_e32 v140, v40, v40
	v_fmac_f32_e32 v141, v41, v41
	v_fmac_f32_e32 v140, v42, v42
	v_fmac_f32_e32 v141, v43, v43
	v_fmac_f32_e32 v140, v44, v44
	v_fmac_f32_e32 v141, v45, v45
	v_fmac_f32_e32 v140, v46, v46
	v_fmac_f32_e32 v141, v47, v47
	v_fmac_f32_e32 v140, v48, v48
	v_fmac_f32_e32 v141, v49, v49
	v_fmac_f32_e32 v140, v50, v50
	v_fmac_f32_e32 v141, v51, v51
	v_fmac_f32_e32 v140, v52, v52
	v_fmac_f32_e32 v141, v53, v53
	v_fmac_f32_e32 v140, v54, v54
	v_fmac_f32_e32 v141, v55, v55
	v_fmac_f32_e32 v140, v56, v56
	v_fmac_f32_e32 v141, v57, v57
	v_fmac_f32_e32 v140, v58, v58
	v_fmac_f32_e32 v141, v59, v59
	v_fmac_f32_e32 v140, v60, v60
	v_fmac_f32_e32 v141, v61, v61
	v_fmac_f32_e32 v140, v62, v62
	v_fmac_f32_e32 v141, v63, v63
	v_add_f32_e32 v140, v140, v141
	s_nop 1
	v_add_f32_dpp v142, v140, v140 quad_perm:[1,0,3,2] row_mask:0xf bank_mask:0xf
	s_nop 1
	v_add_f32_dpp v142, v142, v142 quad_perm:[2,3,0,1] row_mask:0xf bank_mask:0xf
	s_nop 1
	v_add_f32_dpp v142, v142, v142 row_half_mirror row_mask:0xf bank_mask:0xf
	s_nop 1
	v_add_f32_dpp v142, v142, v142 row_mirror row_mask:0xf bank_mask:0xf
	s_nop 1
	v_readlane_b32 s20, v142, 0
	v_readlane_b32 s21, v142, 16
	v_readlane_b32 s22, v142, 32
	v_readlane_b32 s23, v142, 48
	s_nop 1
	v_mov_b32_e32 v143, s20
	v_add_f32_e32 v143, s21, v143
	v_add_f32_e32 v143, s22, v143
	v_add_f32_e32 v143, s23, v143
	v_fmamk_f32 v143, v143, 0x3a000000, v131
	v_rsq_f32_e32 v143, v143
	s_nop 0
	s_add_i32 s4, s6, 3
	s_lshl_b32 s5, s4, 12
	s_add_u32 s14, s84, s5
	s_addc_u32 s15, s85, 0
	s_add_u32 s14, s14, 0x1a800000
	s_addc_u32 s15, s15, 0
	v_mul_f32_e32 v136, v143, v32
	v_mul_f32_e32 v137, v143, v33
	v_mul_f32_e32 v138, v143, v34
	v_mul_f32_e32 v139, v143, v35
	v_fma_f32 v136, v136, v64, v96
	v_fma_f32 v137, v137, v65, v97
	v_fma_f32 v138, v138, v66, v98
	v_fma_f32 v139, v139, v67, v99
	v_cvt_pk_bf16_f32 v132, v136, v137
	v_cvt_pk_bf16_f32 v133, v138, v139
	global_store_dwordx2 v130, v[132:133], s[14:15] offset:0
	v_mul_f32_e32 v136, v143, v36
	v_mul_f32_e32 v137, v143, v37
	v_mul_f32_e32 v138, v143, v38
	v_mul_f32_e32 v139, v143, v39
	v_fma_f32 v136, v136, v68, v100
	v_fma_f32 v137, v137, v69, v101
	v_fma_f32 v138, v138, v70, v102
	v_fma_f32 v139, v139, v71, v103
	v_cvt_pk_bf16_f32 v134, v136, v137
	v_cvt_pk_bf16_f32 v135, v138, v139
	global_store_dwordx2 v130, v[134:135], s[14:15] offset:512
	v_mul_f32_e32 v136, v143, v40
	v_mul_f32_e32 v137, v143, v41
	v_mul_f32_e32 v138, v143, v42
	v_mul_f32_e32 v139, v143, v43
	v_fma_f32 v136, v136, v72, v104
	v_fma_f32 v137, v137, v73, v105
	v_fma_f32 v138, v138, v74, v106
	v_fma_f32 v139, v139, v75, v107
	v_cvt_pk_bf16_f32 v132, v136, v137
	v_cvt_pk_bf16_f32 v133, v138, v139
	global_store_dwordx2 v130, v[132:133], s[14:15] offset:1024
	v_mul_f32_e32 v136, v143, v44
	v_mul_f32_e32 v137, v143, v45
	v_mul_f32_e32 v138, v143, v46
	v_mul_f32_e32 v139, v143, v47
	v_fma_f32 v136, v136, v76, v108
	v_fma_f32 v137, v137, v77, v109
	v_fma_f32 v138, v138, v78, v110
	v_fma_f32 v139, v139, v79, v111
	v_cvt_pk_bf16_f32 v134, v136, v137
	v_cvt_pk_bf16_f32 v135, v138, v139
	global_store_dwordx2 v130, v[134:135], s[14:15] offset:1536
	v_mul_f32_e32 v136, v143, v48
	v_mul_f32_e32 v137, v143, v49
	v_mul_f32_e32 v138, v143, v50
	v_mul_f32_e32 v139, v143, v51
	v_fma_f32 v136, v136, v80, v112
	v_fma_f32 v137, v137, v81, v113
	v_fma_f32 v138, v138, v82, v114
	v_fma_f32 v139, v139, v83, v115
	v_cvt_pk_bf16_f32 v132, v136, v137
	v_cvt_pk_bf16_f32 v133, v138, v139
	global_store_dwordx2 v130, v[132:133], s[14:15] offset:2048
	v_mul_f32_e32 v136, v143, v52
	v_mul_f32_e32 v137, v143, v53
	v_mul_f32_e32 v138, v143, v54
	v_mul_f32_e32 v139, v143, v55
	v_fma_f32 v136, v136, v84, v116
	v_fma_f32 v137, v137, v85, v117
	v_fma_f32 v138, v138, v86, v118
	v_fma_f32 v139, v139, v87, v119
	v_cvt_pk_bf16_f32 v134, v136, v137
	v_cvt_pk_bf16_f32 v135, v138, v139
	global_store_dwordx2 v130, v[134:135], s[14:15] offset:2560
	v_mul_f32_e32 v136, v143, v56
	v_mul_f32_e32 v137, v143, v57
	v_mul_f32_e32 v138, v143, v58
	v_mul_f32_e32 v139, v143, v59
	v_fma_f32 v136, v136, v88, v120
	v_fma_f32 v137, v137, v89, v121
	v_fma_f32 v138, v138, v90, v122
	v_fma_f32 v139, v139, v91, v123
	v_cvt_pk_bf16_f32 v132, v136, v137
	v_cvt_pk_bf16_f32 v133, v138, v139
	global_store_dwordx2 v130, v[132:133], s[14:15] offset:3072
	v_mul_f32_e32 v136, v143, v60
	v_mul_f32_e32 v137, v143, v61
	v_mul_f32_e32 v138, v143, v62
	v_mul_f32_e32 v139, v143, v63
	v_fma_f32 v136, v136, v92, v124
	v_fma_f32 v137, v137, v93, v125
	v_fma_f32 v138, v138, v94, v126
	v_fma_f32 v139, v139, v95, v127
	v_cvt_pk_bf16_f32 v134, v136, v137
	v_cvt_pk_bf16_f32 v135, v138, v139
	global_store_dwordx2 v130, v[134:135], s[14:15] offset:3584
	s_add_i32 s4, s6, 5
	s_cmp_lt_u32 s4, 0x4000
	s_cselect_b32 s10, s68, s72
	s_cselect_b32 s11, s69, s73
	s_cselect_b32 s5, 0, 0x4000
	s_sub_i32 s5, s4, s5
	s_lshl_b32 s5, s5, 13
	s_add_u32 s10, s10, s5
	s_addc_u32 s11, s11, 0
	global_load_dwordx4 v[32:35], v128, s[10:11] offset:0 nt
	global_load_dwordx4 v[36:39], v128, s[10:11] offset:1024 nt
	global_load_dwordx4 v[40:43], v128, s[10:11] offset:2048 nt
	global_load_dwordx4 v[44:47], v128, s[10:11] offset:3072 nt
	global_load_dwordx4 v[48:51], v129, s[10:11] offset:0 nt
	global_load_dwordx4 v[52:55], v129, s[10:11] offset:1024 nt
	global_load_dwordx4 v[56:59], v129, s[10:11] offset:2048 nt
	global_load_dwordx4 v[60:63], v129, s[10:11] offset:3072 nt
	s_add_i32 s4, s6, 4
	s_add_i32 s4, s6, 4
	s_lshr_b32 s8, s4, 11
	s_cmp_lt_u32 s4, 0x4000
	s_cselect_b32 s8, s8, 8
	s_cmp_eq_u32 s8, s7
	s_cbranch_scc1 .Lp1_np4
; __device__ __forceinline__ unsigned cvt_pk_bf16(float lo, float hi) { unsigned r; asm volatile("v_cvt_pk_bf16_f32 %0, %1, %2" : "=v"(r) : "v"(lo), "v"(hi)); return r; }
; __device__ __forceinline__ void modulate_store(const f32x4 (&v)[8], float rstd, const float* pn, const float* modr, bf16_t* orow, int lane) {
; #pragma unroll
;     for (int j = 0; j < 8; ++j) { const int col = 4 * lane + 256 * j;
;         const f32x4 g = *(const f32x4*)(pn + col), sh = *(const f32x4*)(modr + col), sc = *(const f32x4*)(modr + DM + col);
;         const f32x4 hh = v[j] * rstd * g * (sc + 1.f) + sh;
;         u32x2 w; w.x = cvt_pk_bf16(hh[0], hh[1]); w.y = cvt_pk_bf16(hh[2], hh[3]);
;         *(u32x2*)(orow + col) = w; }
; __global__ void __launch_bounds__(NWAVES * 64, 2) mk_fwd(Args args) {
;     ...
;             for (int q = 0; q < 3; ++q) { const int row = row0 + q; const int r = row < ML ? row / SEQ : 8;
;                 const float rstd = __builtin_amdgcn_rsqf(sumsq8(v[q]) * (1.f / DM) + EPS);
	s_mov_b32 s7, s8
	s_add_i32 s5, s8, 0
	s_mul_i32 s5, s5, 0x6000
	s_add_u32 s24, s84, s5
	s_addc_u32 s25, s85, 0
	s_add_u32 s24, s24, 0x2000
	s_addc_u32 s25, s25, 0
	s_add_i32 s5, s8, 0
	s_mul_i32 s5, s5, 0x6000
	s_add_u32 s16, s84, s5
	s_addc_u32 s17, s85, 0
	s_add_u32 s18, s80, 0x0
	s_addc_u32 s19, s81, 0
	global_load_dwordx4 v[64:67], v128, s[18:19] offset:0
	global_load_dwordx4 v[96:99], v128, s[16:17] offset:0
	global_load_dwordx4 v[68:71], v128, s[18:19] offset:1024
	global_load_dwordx4 v[100:103], v128, s[16:17] offset:1024
	global_load_dwordx4 v[72:75], v128, s[18:19] offset:2048
	global_load_dwordx4 v[104:107], v128, s[16:17] offset:2048
	global_load_dwordx4 v[76:79], v128, s[18:19] offset:3072
	global_load_dwordx4 v[108:111], v128, s[16:17] offset:3072
	global_load_dwordx4 v[80:83], v129, s[18:19] offset:0
	global_load_dwordx4 v[112:115], v129, s[16:17] offset:0
	global_load_dwordx4 v[84:87], v129, s[18:19] offset:1024
	global_load_dwordx4 v[116:119], v129, s[16:17] offset:1024
	global_load_dwordx4 v[88:91], v129, s[18:19] offset:2048
	global_load_dwordx4 v[120:123], v129, s[16:17] offset:2048
	global_load_dwordx4 v[92:95], v129, s[18:19] offset:3072
	global_load_dwordx4 v[124:127], v129, s[16:17] offset:3072
	global_load_dwordx4 v[136:139], v128, s[24:25] offset:0
	s_waitcnt vmcnt(0)
	v_add_f32_e32 v136, 1.0, v136
	v_add_f32_e32 v137, 1.0, v137
	v_add_f32_e32 v138, 1.0, v138
	v_add_f32_e32 v139, 1.0, v139
	v_mul_f32_e32 v64, v64, v136
	v_mul_f32_e32 v65, v65, v137
	v_mul_f32_e32 v66, v66, v138
	v_mul_f32_e32 v67, v67, v139
	global_load_dwordx4 v[136:139], v128, s[24:25] offset:1024
	s_waitcnt vmcnt(0)
	v_add_f32_e32 v136, 1.0, v136
	v_add_f32_e32 v137, 1.0, v137
	v_add_f32_e32 v138, 1.0, v138
	v_add_f32_e32 v139, 1.0, v139
	v_mul_f32_e32 v68, v68, v136
	v_mul_f32_e32 v69, v69, v137
	v_mul_f32_e32 v70, v70, v138
	v_mul_f32_e32 v71, v71, v139
	global_load_dwordx4 v[136:139], v128, s[24:25] offset:2048
	s_waitcnt vmcnt(0)
	v_add_f32_e32 v136, 1.0, v136
	v_add_f32_e32 v137, 1.0, v137
	v_add_f32_e32 v138, 1.0, v138
	v_add_f32_e32 v139, 1.0, v139
	v_mul_f32_e32 v72, v72, v136
	v_mul_f32_e32 v73, v73, v137
	v_mul_f32_e32 v74, v74, v138
	v_mul_f32_e32 v75, v75, v139
	global_load_dwordx4 v[136:139], v128, s[24:25] offset:3072
	s_waitcnt vmcnt(0)
	v_add_f32_e32 v136, 1.0, v136
	v_add_f32_e32 v137, 1.0, v137
	v_add_f32_e32 v138, 1.0, v138
	v_add_f32_e32 v139, 1.0, v139
	v_mul_f32_e32 v76, v76, v136
	v_mul_f32_e32 v77, v77, v137
	v_mul_f32_e32 v78, v78, v138
	v_mul_f32_e32 v79, v79, v139
	global_load_dwordx4 v[136:139], v129, s[24:25] offset:0
	s_waitcnt vmcnt(0)
	v_add_f32_e32 v136, 1.0, v136
	v_add_f32_e32 v137, 1.0, v137
	v_add_f32_e32 v138, 1.0, v138
	v_add_f32_e32 v139, 1.0, v139
	v_mul_f32_e32 v80, v80, v136
	v_mul_f32_e32 v81, v81, v137
	v_mul_f32_e32 v82, v82, v138
	v_mul_f32_e32 v83, v83, v139
	global_load_dwordx4 v[136:139], v129, s[24:25] offset:1024
	s_waitcnt vmcnt(0)
	v_add_f32_e32 v136, 1.0, v136
	v_add_f32_e32 v137, 1.0, v137
	v_add_f32_e32 v138, 1.0, v138
	v_add_f32_e32 v139, 1.0, v139
	v_mul_f32_e32 v84, v84, v136
	v_mul_f32_e32 v85, v85, v137
	v_mul_f32_e32 v86, v86, v138
	v_mul_f32_e32 v87, v87, v139
	global_load_dwordx4 v[136:139], v129, s[24:25] offset:2048
	s_waitcnt vmcnt(0)
	v_add_f32_e32 v136, 1.0, v136
	v_add_f32_e32 v137, 1.0, v137
	v_add_f32_e32 v138, 1.0, v138
	v_add_f32_e32 v139, 1.0, v139
	v_mul_f32_e32 v88, v88, v136
	v_mul_f32_e32 v89, v89, v137
	v_mul_f32_e32 v90, v90, v138
	v_mul_f32_e32 v91, v91, v139
	global_load_dwordx4 v[136:139], v129, s[24:25] offset:3072
	s_waitcnt vmcnt(0)
	v_add_f32_e32 v136, 1.0, v136
	v_add_f32_e32 v137, 1.0, v137
	v_add_f32_e32 v138, 1.0, v138
	v_add_f32_e32 v139, 1.0, v139
	v_mul_f32_e32 v92, v92, v136
	v_mul_f32_e32 v93, v93, v137
	v_mul_f32_e32 v94, v94, v138
	v_mul_f32_e32 v95, v95, v139
.Lp1_np4:
	s_waitcnt vmcnt(16)
	v_mul_f32_e32 v140, v0, v0
	v_mul_f32_e32 v141, v1, v1
	v_fmac_f32_e32 v140, v2, v2
	v_fmac_f32_e32 v141, v3, v3
	v_fmac_f32_e32 v140, v4, v4
	v_fmac_f32_e32 v141, v5, v5
	v_fmac_f32_e32 v140, v6, v6
	v_fmac_f32_e32 v141, v7, v7
	v_fmac_f32_e32 v140, v8, v8
	v_fmac_f32_e32 v141, v9, v9
	v_fmac_f32_e32 v140, v10, v10
	v_fmac_f32_e32 v141, v11, v11
	v_fmac_f32_e32 v140, v12, v12
	v_fmac_f32_e32 v141, v13, v13
	v_fmac_f32_e32 v140, v14, v14
	v_fmac_f32_e32 v141, v15, v15
	v_fmac_f32_e32 v140, v16, v16
	v_fmac_f32_e32 v141, v17, v17
	v_fmac_f32_e32 v140, v18, v18
	v_fmac_f32_e32 v141, v19, v19
	v_fmac_f32_e32 v140, v20, v20
	v_fmac_f32_e32 v141, v21, v21
	v_fmac_f32_e32 v140, v22, v22
	v_fmac_f32_e32 v141, v23, v23
	v_fmac_f32_e32 v140, v24, v24
	v_fmac_f32_e32 v141, v25, v25
	v_fmac_f32_e32 v140, v26, v26
	v_fmac_f32_e32 v141, v27, v27
	v_fmac_f32_e32 v140, v28, v28
	v_fmac_f32_e32 v141, v29, v29
	v_fmac_f32_e32 v140, v30, v30
	v_fmac_f32_e32 v141, v31, v31
	v_add_f32_e32 v140, v140, v141
	s_nop 1
	v_add_f32_dpp v142, v140, v140 quad_perm:[1,0,3,2] row_mask:0xf bank_mask:0xf
	s_nop 1
	v_add_f32_dpp v142, v142, v142 quad_perm:[2,3,0,1] row_mask:0xf bank_mask:0xf
	s_nop 1
	v_add_f32_dpp v142, v142, v142 row_half_mirror row_mask:0xf bank_mask:0xf
	s_nop 1
	v_add_f32_dpp v142, v142, v142 row_mirror row_mask:0xf bank_mask:0xf
	s_nop 1
	v_readlane_b32 s20, v142, 0
	v_readlane_b32 s21, v142, 16
	v_readlane_b32 s22, v142, 32
	v_readlane_b32 s23, v142, 48
	s_nop 1
	v_mov_b32_e32 v143, s20
	v_add_f32_e32 v143, s21, v143
	v_add_f32_e32 v143, s22, v143
	v_add_f32_e32 v143, s23, v143
	v_fmamk_f32 v143, v143, 0x3a000000, v131
	v_rsq_f32_e32 v143, v143
	s_nop 0
	s_add_i32 s4, s6, 4
	s_lshl_b32 s5, s4, 12
	s_add_u32 s14, s84, s5
	s_addc_u32 s15, s85, 0
	s_add_u32 s14, s14, 0x1a800000
; __device__ __forceinline__ unsigned cvt_pk_bf16(float lo, float hi) { unsigned r; asm volatile("v_cvt_pk_bf16_f32 %0, %1, %2" : "=v"(r) : "v"(lo), "v"(hi)); return r; }
; __device__ __forceinline__ void modulate_store(const f32x4 (&v)[8], float rstd, const float* pn, const float* modr, bf16_t* orow, int lane) {
; #pragma unroll
;     for (int j = 0; j < 8; ++j) { const int col = 4 * lane + 256 * j;
;         const f32x4 g = *(const f32x4*)(pn + col), sh = *(const f32x4*)(modr + col), sc = *(const f32x4*)(modr + DM + col);
;         const f32x4 hh = v[j] * rstd * g * (sc + 1.f) + sh;
;         u32x2 w; w.x = cvt_pk_bf16(hh[0], hh[1]); w.y = cvt_pk_bf16(hh[2], hh[3]);
;         *(u32x2*)(orow + col) = w; }
; __global__ void __launch_bounds__(NWAVES * 64, 2) mk_fwd(Args args) {
;     ...
;             for (int q = 0; q < 3; ++q) { const int row = row0 + q; const float* src = row < ML ? x + (size_t)row * DM : ctx + (size_t)(row - ML) * DM; load_row_f32(src, F.lane, v[q]); }
	s_addc_u32 s15, s15, 0
	v_mul_f32_e32 v136, v143, v0
	v_mul_f32_e32 v137, v143, v1
	v_mul_f32_e32 v138, v143, v2
	v_mul_f32_e32 v139, v143, v3
	v_fma_f32 v136, v136, v64, v96
	v_fma_f32 v137, v137, v65, v97
	v_fma_f32 v138, v138, v66, v98
	v_fma_f32 v139, v139, v67, v99
	v_cvt_pk_bf16_f32 v132, v136, v137
	v_cvt_pk_bf16_f32 v133, v138, v139
	global_store_dwordx2 v130, v[132:133], s[14:15] offset:0
	v_mul_f32_e32 v136, v143, v4
	v_mul_f32_e32 v137, v143, v5
	v_mul_f32_e32 v138, v143, v6
	v_mul_f32_e32 v139, v143, v7
	v_fma_f32 v136, v136, v68, v100
	v_fma_f32 v137, v137, v69, v101
	v_fma_f32 v138, v138, v70, v102
	v_fma_f32 v139, v139, v71, v103
	v_cvt_pk_bf16_f32 v134, v136, v137
	v_cvt_pk_bf16_f32 v135, v138, v139
	global_store_dwordx2 v130, v[134:135], s[14:15] offset:512
	v_mul_f32_e32 v136, v143, v8
	v_mul_f32_e32 v137, v143, v9
	v_mul_f32_e32 v138, v143, v10
	v_mul_f32_e32 v139, v143, v11
	v_fma_f32 v136, v136, v72, v104
	v_fma_f32 v137, v137, v73, v105
	v_fma_f32 v138, v138, v74, v106
	v_fma_f32 v139, v139, v75, v107
	v_cvt_pk_bf16_f32 v132, v136, v137
	v_cvt_pk_bf16_f32 v133, v138, v139
	global_store_dwordx2 v130, v[132:133], s[14:15] offset:1024
	v_mul_f32_e32 v136, v143, v12
	v_mul_f32_e32 v137, v143, v13
	v_mul_f32_e32 v138, v143, v14
	v_mul_f32_e32 v139, v143, v15
	v_fma_f32 v136, v136, v76, v108
	v_fma_f32 v137, v137, v77, v109
	v_fma_f32 v138, v138, v78, v110
	v_fma_f32 v139, v139, v79, v111
	v_cvt_pk_bf16_f32 v134, v136, v137
	v_cvt_pk_bf16_f32 v135, v138, v139
	global_store_dwordx2 v130, v[134:135], s[14:15] offset:1536
	v_mul_f32_e32 v136, v143, v16
	v_mul_f32_e32 v137, v143, v17
	v_mul_f32_e32 v138, v143, v18
	v_mul_f32_e32 v139, v143, v19
	v_fma_f32 v136, v136, v80, v112
	v_fma_f32 v137, v137, v81, v113
	v_fma_f32 v138, v138, v82, v114
	v_fma_f32 v139, v139, v83, v115
	v_cvt_pk_bf16_f32 v132, v136, v137
	v_cvt_pk_bf16_f32 v133, v138, v139
	global_store_dwordx2 v130, v[132:133], s[14:15] offset:2048
	v_mul_f32_e32 v136, v143, v20
	v_mul_f32_e32 v137, v143, v21
	v_mul_f32_e32 v138, v143, v22
	v_mul_f32_e32 v139, v143, v23
	v_fma_f32 v136, v136, v84, v116
	v_fma_f32 v137, v137, v85, v117
	v_fma_f32 v138, v138, v86, v118
	v_fma_f32 v139, v139, v87, v119
	v_cvt_pk_bf16_f32 v134, v136, v137
	v_cvt_pk_bf16_f32 v135, v138, v139
	global_store_dwordx2 v130, v[134:135], s[14:15] offset:2560
	v_mul_f32_e32 v136, v143, v24
	v_mul_f32_e32 v137, v143, v25
	v_mul_f32_e32 v138, v143, v26
	v_mul_f32_e32 v139, v143, v27
	v_fma_f32 v136, v136, v88, v120
	v_fma_f32 v137, v137, v89, v121
	v_fma_f32 v138, v138, v90, v122
	v_fma_f32 v139, v139, v91, v123
	v_cvt_pk_bf16_f32 v132, v136, v137
	v_cvt_pk_bf16_f32 v133, v138, v139
	global_store_dwordx2 v130, v[132:133], s[14:15] offset:3072
	v_mul_f32_e32 v136, v143, v28
	v_mul_f32_e32 v137, v143, v29
	v_mul_f32_e32 v138, v143, v30
	v_mul_f32_e32 v139, v143, v31
	v_fma_f32 v136, v136, v92, v124
	v_fma_f32 v137, v137, v93, v125
	v_fma_f32 v138, v138, v94, v126
	v_fma_f32 v139, v139, v95, v127
	v_cvt_pk_bf16_f32 v134, v136, v137
	v_cvt_pk_bf16_f32 v135, v138, v139
	global_store_dwordx2 v130, v[134:135], s[14:15] offset:3584
	s_add_i32 s4, s6, 6
	s_cmp_lt_u32 s4, 0x4000
	s_cselect_b32 s10, s68, s72
	s_cselect_b32 s11, s69, s73
	s_cselect_b32 s5, 0, 0x4000
	s_sub_i32 s5, s4, s5
	s_lshl_b32 s5, s5, 13
	s_add_u32 s10, s10, s5
	s_addc_u32 s11, s11, 0
	global_load_dwordx4 v[0:3], v128, s[10:11] offset:0 nt
	global_load_dwordx4 v[4:7], v128, s[10:11] offset:1024 nt
	global_load_dwordx4 v[8:11], v128, s[10:11] offset:2048 nt
	global_load_dwordx4 v[12:15], v128, s[10:11] offset:3072 nt
	global_load_dwordx4 v[16:19], v129, s[10:11] offset:0 nt
	global_load_dwordx4 v[20:23], v129, s[10:11] offset:1024 nt
	global_load_dwordx4 v[24:27], v129, s[10:11] offset:2048 nt
	global_load_dwordx4 v[28:31], v129, s[10:11] offset:3072 nt
	s_add_i32 s4, s6, 5
	s_add_i32 s4, s6, 5
	s_lshr_b32 s8, s4, 11
	s_cmp_lt_u32 s4, 0x4000
	s_cselect_b32 s8, s8, 8
	s_cmp_eq_u32 s8, s7
	s_cbranch_scc1 .Lp1_np5
	s_mov_b32 s7, s8
	s_add_i32 s5, s8, 0
	s_mul_i32 s5, s5, 0x6000
	s_add_u32 s24, s84, s5
	s_addc_u32 s25, s85, 0
	s_add_u32 s24, s24, 0x2000
	s_addc_u32 s25, s25, 0
	s_add_i32 s5, s8, 0
	s_mul_i32 s5, s5, 0x6000
	s_add_u32 s16, s84, s5
	s_addc_u32 s17, s85, 0
	s_add_u32 s18, s80, 0x0
	s_addc_u32 s19, s81, 0
	global_load_dwordx4 v[64:67], v128, s[18:19] offset:0
	global_load_dwordx4 v[96:99], v128, s[16:17] offset:0
	global_load_dwordx4 v[68:71], v128, s[18:19] offset:1024
	global_load_dwordx4 v[100:103], v128, s[16:17] offset:1024
	global_load_dwordx4 v[72:75], v128, s[18:19] offset:2048
	global_load_dwordx4 v[104:107], v128, s[16:17] offset:2048
	global_load_dwordx4 v[76:79], v128, s[18:19] offset:3072
	global_load_dwordx4 v[108:111], v128, s[16:17] offset:3072
	global_load_dwordx4 v[80:83], v129, s[18:19] offset:0
	global_load_dwordx4 v[112:115], v129, s[16:17] offset:0
	global_load_dwordx4 v[84:87], v129, s[18:19] offset:1024
	global_load_dwordx4 v[116:119], v129, s[16:17] offset:1024
	global_load_dwordx4 v[88:91], v129, s[18:19] offset:2048
	global_load_dwordx4 v[120:123], v129, s[16:17] offset:2048
	global_load_dwordx4 v[92:95], v129, s[18:19] offset:3072
	global_load_dwordx4 v[124:127], v129, s[16:17] offset:3072
	global_load_dwordx4 v[136:139], v128, s[24:25] offset:0
	s_waitcnt vmcnt(0)
	v_add_f32_e32 v136, 1.0, v136
	v_add_f32_e32 v137, 1.0, v137
	v_add_f32_e32 v138, 1.0, v138
	v_add_f32_e32 v139, 1.0, v139
	v_mul_f32_e32 v64, v64, v136
	v_mul_f32_e32 v65, v65, v137
	v_mul_f32_e32 v66, v66, v138
	v_mul_f32_e32 v67, v67, v139
	global_load_dwordx4 v[136:139], v128, s[24:25] offset:1024
	s_waitcnt vmcnt(0)
; __device__ __forceinline__ unsigned cvt_pk_bf16(float lo, float hi) { unsigned r; asm volatile("v_cvt_pk_bf16_f32 %0, %1, %2" : "=v"(r) : "v"(lo), "v"(hi)); return r; }
; __device__ __forceinline__ float sumsq8(const f32x4 (&v)[8]) {
;     float s = 0.f;
; #pragma unroll
;     for (int j = 0; j < 8; ++j) s += (v[j][0] * v[j][0] + v[j][1] * v[j][1]) + (v[j][2] * v[j][2] + v[j][3] * v[j][3]);
;     return wave_sum(s);
; }
; __device__ __forceinline__ void modulate_store(const f32x4 (&v)[8], float rstd, const float* pn, const float* modr, bf16_t* orow, int lane) {
; #pragma unroll
;     for (int j = 0; j < 8; ++j) { const int col = 4 * lane + 256 * j;
;         const f32x4 g = *(const f32x4*)(pn + col), sh = *(const f32x4*)(modr + col), sc = *(const f32x4*)(modr + DM + col);
;         const f32x4 hh = v[j] * rstd * g * (sc + 1.f) + sh;
;         u32x2 w; w.x = cvt_pk_bf16(hh[0], hh[1]); w.y = cvt_pk_bf16(hh[2], hh[3]);
;         *(u32x2*)(orow + col) = w; }
; __global__ void __launch_bounds__(NWAVES * 64, 2) mk_fwd(Args args) {
;     ...
;             for (int q = 0; q < 3; ++q) { const int row = row0 + q; const int r = row < ML ? row / SEQ : 8;
;                 const float rstd = __builtin_amdgcn_rsqf(sumsq8(v[q]) * (1.f / DM) + EPS);
;                 modulate_store(v[q], rstd, pre_norm, mod + (size_t)r * 6144, H + (size_t)row * DM, F.lane); }
	v_add_f32_e32 v136, 1.0, v136
	v_add_f32_e32 v137, 1.0, v137
	v_add_f32_e32 v138, 1.0, v138
	v_add_f32_e32 v139, 1.0, v139
	v_mul_f32_e32 v68, v68, v136
	v_mul_f32_e32 v69, v69, v137
	v_mul_f32_e32 v70, v70, v138
	v_mul_f32_e32 v71, v71, v139
	global_load_dwordx4 v[136:139], v128, s[24:25] offset:2048
	s_waitcnt vmcnt(0)
	v_add_f32_e32 v136, 1.0, v136
	v_add_f32_e32 v137, 1.0, v137
	v_add_f32_e32 v138, 1.0, v138
	v_add_f32_e32 v139, 1.0, v139
	v_mul_f32_e32 v72, v72, v136
	v_mul_f32_e32 v73, v73, v137
	v_mul_f32_e32 v74, v74, v138
	v_mul_f32_e32 v75, v75, v139
	global_load_dwordx4 v[136:139], v128, s[24:25] offset:3072
	s_waitcnt vmcnt(0)
	v_add_f32_e32 v136, 1.0, v136
	v_add_f32_e32 v137, 1.0, v137
	v_add_f32_e32 v138, 1.0, v138
	v_add_f32_e32 v139, 1.0, v139
	v_mul_f32_e32 v76, v76, v136
	v_mul_f32_e32 v77, v77, v137
	v_mul_f32_e32 v78, v78, v138
	v_mul_f32_e32 v79, v79, v139
	global_load_dwordx4 v[136:139], v129, s[24:25] offset:0
	s_waitcnt vmcnt(0)
	v_add_f32_e32 v136, 1.0, v136
	v_add_f32_e32 v137, 1.0, v137
	v_add_f32_e32 v138, 1.0, v138
	v_add_f32_e32 v139, 1.0, v139
	v_mul_f32_e32 v80, v80, v136
	v_mul_f32_e32 v81, v81, v137
	v_mul_f32_e32 v82, v82, v138
	v_mul_f32_e32 v83, v83, v139
	global_load_dwordx4 v[136:139], v129, s[24:25] offset:1024
	s_waitcnt vmcnt(0)
	v_add_f32_e32 v136, 1.0, v136
	v_add_f32_e32 v137, 1.0, v137
	v_add_f32_e32 v138, 1.0, v138
	v_add_f32_e32 v139, 1.0, v139
	v_mul_f32_e32 v84, v84, v136
	v_mul_f32_e32 v85, v85, v137
	v_mul_f32_e32 v86, v86, v138
	v_mul_f32_e32 v87, v87, v139
	global_load_dwordx4 v[136:139], v129, s[24:25] offset:2048
	s_waitcnt vmcnt(0)
	v_add_f32_e32 v136, 1.0, v136
	v_add_f32_e32 v137, 1.0, v137
	v_add_f32_e32 v138, 1.0, v138
	v_add_f32_e32 v139, 1.0, v139
	v_mul_f32_e32 v88, v88, v136
	v_mul_f32_e32 v89, v89, v137
	v_mul_f32_e32 v90, v90, v138
	v_mul_f32_e32 v91, v91, v139
	global_load_dwordx4 v[136:139], v129, s[24:25] offset:3072
	s_waitcnt vmcnt(0)
	v_add_f32_e32 v136, 1.0, v136
	v_add_f32_e32 v137, 1.0, v137
	v_add_f32_e32 v138, 1.0, v138
	v_add_f32_e32 v139, 1.0, v139
	v_mul_f32_e32 v92, v92, v136
	v_mul_f32_e32 v93, v93, v137
	v_mul_f32_e32 v94, v94, v138
	v_mul_f32_e32 v95, v95, v139
.Lp1_np5:
	s_waitcnt vmcnt(16)
	v_mul_f32_e32 v140, v32, v32
	v_mul_f32_e32 v141, v33, v33
	v_fmac_f32_e32 v140, v34, v34
	v_fmac_f32_e32 v141, v35, v35
	v_fmac_f32_e32 v140, v36, v36
	v_fmac_f32_e32 v141, v37, v37
	v_fmac_f32_e32 v140, v38, v38
	v_fmac_f32_e32 v141, v39, v39
	v_fmac_f32_e32 v140, v40, v40
	v_fmac_f32_e32 v141, v41, v41
	v_fmac_f32_e32 v140, v42, v42
	v_fmac_f32_e32 v141, v43, v43
	v_fmac_f32_e32 v140, v44, v44
	v_fmac_f32_e32 v141, v45, v45
	v_fmac_f32_e32 v140, v46, v46
	v_fmac_f32_e32 v141, v47, v47
	v_fmac_f32_e32 v140, v48, v48
	v_fmac_f32_e32 v141, v49, v49
	v_fmac_f32_e32 v140, v50, v50
	v_fmac_f32_e32 v141, v51, v51
	v_fmac_f32_e32 v140, v52, v52
	v_fmac_f32_e32 v141, v53, v53
	v_fmac_f32_e32 v140, v54, v54
	v_fmac_f32_e32 v141, v55, v55
	v_fmac_f32_e32 v140, v56, v56
	v_fmac_f32_e32 v141, v57, v57
	v_fmac_f32_e32 v140, v58, v58
	v_fmac_f32_e32 v141, v59, v59
	v_fmac_f32_e32 v140, v60, v60
	v_fmac_f32_e32 v141, v61, v61
	v_fmac_f32_e32 v140, v62, v62
	v_fmac_f32_e32 v141, v63, v63
	v_add_f32_e32 v140, v140, v141
	s_nop 1
	v_add_f32_dpp v142, v140, v140 quad_perm:[1,0,3,2] row_mask:0xf bank_mask:0xf
	s_nop 1
	v_add_f32_dpp v142, v142, v142 quad_perm:[2,3,0,1] row_mask:0xf bank_mask:0xf
	s_nop 1
	v_add_f32_dpp v142, v142, v142 row_half_mirror row_mask:0xf bank_mask:0xf
	s_nop 1
	v_add_f32_dpp v142, v142, v142 row_mirror row_mask:0xf bank_mask:0xf
	s_nop 1
	v_readlane_b32 s20, v142, 0
	v_readlane_b32 s21, v142, 16
	v_readlane_b32 s22, v142, 32
	v_readlane_b32 s23, v142, 48
	s_nop 1
	v_mov_b32_e32 v143, s20
	v_add_f32_e32 v143, s21, v143
	v_add_f32_e32 v143, s22, v143
	v_add_f32_e32 v143, s23, v143
	v_fmamk_f32 v143, v143, 0x3a000000, v131
	v_rsq_f32_e32 v143, v143
	s_nop 0
	s_add_i32 s4, s6, 5
	s_lshl_b32 s5, s4, 12
	s_add_u32 s14, s84, s5
	s_addc_u32 s15, s85, 0
	s_add_u32 s14, s14, 0x1a800000
	s_addc_u32 s15, s15, 0
	v_mul_f32_e32 v136, v143, v32
	v_mul_f32_e32 v137, v143, v33
	v_mul_f32_e32 v138, v143, v34
	v_mul_f32_e32 v139, v143, v35
	v_fma_f32 v136, v136, v64, v96
	v_fma_f32 v137, v137, v65, v97
	v_fma_f32 v138, v138, v66, v98
	v_fma_f32 v139, v139, v67, v99
	v_cvt_pk_bf16_f32 v132, v136, v137
	v_cvt_pk_bf16_f32 v133, v138, v139
	global_store_dwordx2 v130, v[132:133], s[14:15] offset:0
	v_mul_f32_e32 v136, v143, v36
	v_mul_f32_e32 v137, v143, v37
	v_mul_f32_e32 v138, v143, v38
	v_mul_f32_e32 v139, v143, v39
	v_fma_f32 v136, v136, v68, v100
	v_fma_f32 v137, v137, v69, v101
	v_fma_f32 v138, v138, v70, v102
	v_fma_f32 v139, v139, v71, v103
	v_cvt_pk_bf16_f32 v134, v136, v137
	v_cvt_pk_bf16_f32 v135, v138, v139
	global_store_dwordx2 v130, v[134:135], s[14:15] offset:512
	v_mul_f32_e32 v136, v143, v40
	v_mul_f32_e32 v137, v143, v41
	v_mul_f32_e32 v138, v143, v42
	v_mul_f32_e32 v139, v143, v43
	v_fma_f32 v136, v136, v72, v104
	v_fma_f32 v137, v137, v73, v105
	v_fma_f32 v138, v138, v74, v106
	v_fma_f32 v139, v139, v75, v107
	v_cvt_pk_bf16_f32 v132, v136, v137
	v_cvt_pk_bf16_f32 v133, v138, v139
	global_store_dwordx2 v130, v[132:133], s[14:15] offset:1024
	v_mul_f32_e32 v136, v143, v44
	v_mul_f32_e32 v137, v143, v45
	v_mul_f32_e32 v138, v143, v46
	v_mul_f32_e32 v139, v143, v47
	v_fma_f32 v136, v136, v76, v108
	v_fma_f32 v137, v137, v77, v109
	v_fma_f32 v138, v138, v78, v110
	v_fma_f32 v139, v139, v79, v111
	v_cvt_pk_bf16_f32 v134, v136, v137
	v_cvt_pk_bf16_f32 v135, v138, v139
	global_store_dwordx2 v130, v[134:135], s[14:15] offset:1536
	v_mul_f32_e32 v136, v143, v48
; __device__ __forceinline__ unsigned cvt_pk_bf16(float lo, float hi) { unsigned r; asm volatile("v_cvt_pk_bf16_f32 %0, %1, %2" : "=v"(r) : "v"(lo), "v"(hi)); return r; }
; __device__ __forceinline__ void modulate_store(const f32x4 (&v)[8], float rstd, const float* pn, const float* modr, bf16_t* orow, int lane) {
; #pragma unroll
;     for (int j = 0; j < 8; ++j) { const int col = 4 * lane + 256 * j;
;         const f32x4 g = *(const f32x4*)(pn + col), sh = *(const f32x4*)(modr + col), sc = *(const f32x4*)(modr + DM + col);
;         const f32x4 hh = v[j] * rstd * g * (sc + 1.f) + sh;
;         u32x2 w; w.x = cvt_pk_bf16(hh[0], hh[1]); w.y = cvt_pk_bf16(hh[2], hh[3]);
;         *(u32x2*)(orow + col) = w; }
; __global__ void __launch_bounds__(NWAVES * 64, 2) mk_fwd(Args args) {
;     ...
;             for (int q = 0; q < 3; ++q) { const int row = row0 + q; const float* src = row < ML ? x + (size_t)row * DM : ctx + (size_t)(row - ML) * DM; load_row_f32(src, F.lane, v[q]); }
	v_mul_f32_e32 v137, v143, v49
	v_mul_f32_e32 v138, v143, v50
	v_mul_f32_e32 v139, v143, v51
	v_fma_f32 v136, v136, v80, v112
	v_fma_f32 v137, v137, v81, v113
	v_fma_f32 v138, v138, v82, v114
	v_fma_f32 v139, v139, v83, v115
	v_cvt_pk_bf16_f32 v132, v136, v137
	v_cvt_pk_bf16_f32 v133, v138, v139
	global_store_dwordx2 v130, v[132:133], s[14:15] offset:2048
	v_mul_f32_e32 v136, v143, v52
	v_mul_f32_e32 v137, v143, v53
	v_mul_f32_e32 v138, v143, v54
	v_mul_f32_e32 v139, v143, v55
	v_fma_f32 v136, v136, v84, v116
	v_fma_f32 v137, v137, v85, v117
	v_fma_f32 v138, v138, v86, v118
	v_fma_f32 v139, v139, v87, v119
	v_cvt_pk_bf16_f32 v134, v136, v137
	v_cvt_pk_bf16_f32 v135, v138, v139
	global_store_dwordx2 v130, v[134:135], s[14:15] offset:2560
	v_mul_f32_e32 v136, v143, v56
	v_mul_f32_e32 v137, v143, v57
	v_mul_f32_e32 v138, v143, v58
	v_mul_f32_e32 v139, v143, v59
	v_fma_f32 v136, v136, v88, v120
	v_fma_f32 v137, v137, v89, v121
	v_fma_f32 v138, v138, v90, v122
	v_fma_f32 v139, v139, v91, v123
	v_cvt_pk_bf16_f32 v132, v136, v137
	v_cvt_pk_bf16_f32 v133, v138, v139
	global_store_dwordx2 v130, v[132:133], s[14:15] offset:3072
	v_mul_f32_e32 v136, v143, v60
	v_mul_f32_e32 v137, v143, v61
	v_mul_f32_e32 v138, v143, v62
	v_mul_f32_e32 v139, v143, v63
	v_fma_f32 v136, v136, v92, v124
	v_fma_f32 v137, v137, v93, v125
	v_fma_f32 v138, v138, v94, v126
	v_fma_f32 v139, v139, v95, v127
	v_cvt_pk_bf16_f32 v134, v136, v137
	v_cvt_pk_bf16_f32 v135, v138, v139
	global_store_dwordx2 v130, v[134:135], s[14:15] offset:3584
	s_add_i32 s4, s6, 7
	s_cmp_lt_u32 s4, 0x4000
	s_cselect_b32 s10, s68, s72
	s_cselect_b32 s11, s69, s73
	s_cselect_b32 s5, 0, 0x4000
	s_sub_i32 s5, s4, s5
	s_lshl_b32 s5, s5, 13
	s_add_u32 s10, s10, s5
	s_addc_u32 s11, s11, 0
	global_load_dwordx4 v[32:35], v128, s[10:11] offset:0 nt
	global_load_dwordx4 v[36:39], v128, s[10:11] offset:1024 nt
	global_load_dwordx4 v[40:43], v128, s[10:11] offset:2048 nt
	global_load_dwordx4 v[44:47], v128, s[10:11] offset:3072 nt
	global_load_dwordx4 v[48:51], v129, s[10:11] offset:0 nt
	global_load_dwordx4 v[52:55], v129, s[10:11] offset:1024 nt
	global_load_dwordx4 v[56:59], v129, s[10:11] offset:2048 nt
	global_load_dwordx4 v[60:63], v129, s[10:11] offset:3072 nt
	s_add_i32 s4, s6, 6
	s_add_i32 s4, s6, 6
	s_lshr_b32 s8, s4, 11
	s_cmp_lt_u32 s4, 0x4000
	s_cselect_b32 s8, s8, 8
	s_cmp_eq_u32 s8, s7
	s_cbranch_scc1 .Lp1_np6
	s_mov_b32 s7, s8
	s_add_i32 s5, s8, 0
	s_mul_i32 s5, s5, 0x6000
	s_add_u32 s24, s84, s5
	s_addc_u32 s25, s85, 0
	s_add_u32 s24, s24, 0x2000
	s_addc_u32 s25, s25, 0
	s_add_i32 s5, s8, 0
	s_mul_i32 s5, s5, 0x6000
	s_add_u32 s16, s84, s5
	s_addc_u32 s17, s85, 0
	s_add_u32 s18, s80, 0x0
	s_addc_u32 s19, s81, 0
	global_load_dwordx4 v[64:67], v128, s[18:19] offset:0
	global_load_dwordx4 v[96:99], v128, s[16:17] offset:0
	global_load_dwordx4 v[68:71], v128, s[18:19] offset:1024
	global_load_dwordx4 v[100:103], v128, s[16:17] offset:1024
	global_load_dwordx4 v[72:75], v128, s[18:19] offset:2048
	global_load_dwordx4 v[104:107], v128, s[16:17] offset:2048
	global_load_dwordx4 v[76:79], v128, s[18:19] offset:3072
	global_load_dwordx4 v[108:111], v128, s[16:17] offset:3072
	global_load_dwordx4 v[80:83], v129, s[18:19] offset:0
	global_load_dwordx4 v[112:115], v129, s[16:17] offset:0
	global_load_dwordx4 v[84:87], v129, s[18:19] offset:1024
	global_load_dwordx4 v[116:119], v129, s[16:17] offset:1024
	global_load_dwordx4 v[88:91], v129, s[18:19] offset:2048
	global_load_dwordx4 v[120:123], v129, s[16:17] offset:2048
	global_load_dwordx4 v[92:95], v129, s[18:19] offset:3072
	global_load_dwordx4 v[124:127], v129, s[16:17] offset:3072
	global_load_dwordx4 v[136:139], v128, s[24:25] offset:0
	s_waitcnt vmcnt(0)
	v_add_f32_e32 v136, 1.0, v136
	v_add_f32_e32 v137, 1.0, v137
	v_add_f32_e32 v138, 1.0, v138
	v_add_f32_e32 v139, 1.0, v139
	v_mul_f32_e32 v64, v64, v136
	v_mul_f32_e32 v65, v65, v137
	v_mul_f32_e32 v66, v66, v138
	v_mul_f32_e32 v67, v67, v139
	global_load_dwordx4 v[136:139], v128, s[24:25] offset:1024
	s_waitcnt vmcnt(0)
	v_add_f32_e32 v136, 1.0, v136
	v_add_f32_e32 v137, 1.0, v137
	v_add_f32_e32 v138, 1.0, v138
	v_add_f32_e32 v139, 1.0, v139
	v_mul_f32_e32 v68, v68, v136
	v_mul_f32_e32 v69, v69, v137
	v_mul_f32_e32 v70, v70, v138
	v_mul_f32_e32 v71, v71, v139
	global_load_dwordx4 v[136:139], v128, s[24:25] offset:2048
	s_waitcnt vmcnt(0)
	v_add_f32_e32 v136, 1.0, v136
	v_add_f32_e32 v137, 1.0, v137
	v_add_f32_e32 v138, 1.0, v138
	v_add_f32_e32 v139, 1.0, v139
	v_mul_f32_e32 v72, v72, v136
	v_mul_f32_e32 v73, v73, v137
	v_mul_f32_e32 v74, v74, v138
	v_mul_f32_e32 v75, v75, v139
	global_load_dwordx4 v[136:139], v128, s[24:25] offset:3072
	s_waitcnt vmcnt(0)
	v_add_f32_e32 v136, 1.0, v136
	v_add_f32_e32 v137, 1.0, v137
	v_add_f32_e32 v138, 1.0, v138
	v_add_f32_e32 v139, 1.0, v139
	v_mul_f32_e32 v76, v76, v136
	v_mul_f32_e32 v77, v77, v137
	v_mul_f32_e32 v78, v78, v138
	v_mul_f32_e32 v79, v79, v139
	global_load_dwordx4 v[136:139], v129, s[24:25] offset:0
	s_waitcnt vmcnt(0)
	v_add_f32_e32 v136, 1.0, v136
	v_add_f32_e32 v137, 1.0, v137
	v_add_f32_e32 v138, 1.0, v138
	v_add_f32_e32 v139, 1.0, v139
	v_mul_f32_e32 v80, v80, v136
	v_mul_f32_e32 v81, v81, v137
	v_mul_f32_e32 v82, v82, v138
	v_mul_f32_e32 v83, v83, v139
	global_load_dwordx4 v[136:139], v129, s[24:25] offset:1024
	s_waitcnt vmcnt(0)
	v_add_f32_e32 v136, 1.0, v136
	v_add_f32_e32 v137, 1.0, v137
	v_add_f32_e32 v138, 1.0, v138
	v_add_f32_e32 v139, 1.0, v139
	v_mul_f32_e32 v84, v84, v136
	v_mul_f32_e32 v85, v85, v137
	v_mul_f32_e32 v86, v86, v138
	v_mul_f32_e32 v87, v87, v139
	global_load_dwordx4 v[136:139], v129, s[24:25] offset:2048
	s_waitcnt vmcnt(0)
	v_add_f32_e32 v136, 1.0, v136
	v_add_f32_e32 v137, 1.0, v137
	v_add_f32_e32 v138, 1.0, v138
	v_add_f32_e32 v139, 1.0, v139
	v_mul_f32_e32 v88, v88, v136
	v_mul_f32_e32 v89, v89, v137
	v_mul_f32_e32 v90, v90, v138
	v_mul_f32_e32 v91, v91, v139
	global_load_dwordx4 v[136:139], v129, s[24:25] offset:3072
	s_waitcnt vmcnt(0)
	v_add_f32_e32 v136, 1.0, v136
	v_add_f32_e32 v137, 1.0, v137
	v_add_f32_e32 v138, 1.0, v138
	v_add_f32_e32 v139, 1.0, v139
	v_mul_f32_e32 v92, v92, v136
	v_mul_f32_e32 v93, v93, v137
	v_mul_f32_e32 v94, v94, v138
	v_mul_f32_e32 v95, v95, v139
; __device__ __forceinline__ unsigned cvt_pk_bf16(float lo, float hi) { unsigned r; asm volatile("v_cvt_pk_bf16_f32 %0, %1, %2" : "=v"(r) : "v"(lo), "v"(hi)); return r; }
; __device__ __forceinline__ float sumsq8(const f32x4 (&v)[8]) {
;     float s = 0.f;
; #pragma unroll
;     for (int j = 0; j < 8; ++j) s += (v[j][0] * v[j][0] + v[j][1] * v[j][1]) + (v[j][2] * v[j][2] + v[j][3] * v[j][3]);
;     return wave_sum(s);
; }
; __device__ __forceinline__ void modulate_store(const f32x4 (&v)[8], float rstd, const float* pn, const float* modr, bf16_t* orow, int lane) {
; #pragma unroll
;     for (int j = 0; j < 8; ++j) { const int col = 4 * lane + 256 * j;
;         const f32x4 g = *(const f32x4*)(pn + col), sh = *(const f32x4*)(modr + col), sc = *(const f32x4*)(modr + DM + col);
;         const f32x4 hh = v[j] * rstd * g * (sc + 1.f) + sh;
;         u32x2 w; w.x = cvt_pk_bf16(hh[0], hh[1]); w.y = cvt_pk_bf16(hh[2], hh[3]);
;         *(u32x2*)(orow + col) = w; }
; __global__ void __launch_bounds__(NWAVES * 64, 2) mk_fwd(Args args) {
;     ...
;             for (int q = 0; q < 3; ++q) { const int row = row0 + q; const int r = row < ML ? row / SEQ : 8;
;                 const float rstd = __builtin_amdgcn_rsqf(sumsq8(v[q]) * (1.f / DM) + EPS);
;                 modulate_store(v[q], rstd, pre_norm, mod + (size_t)r * 6144, H + (size_t)row * DM, F.lane); }
.Lp1_np6:
	s_waitcnt vmcnt(16)
	v_mul_f32_e32 v140, v0, v0
	v_mul_f32_e32 v141, v1, v1
	v_fmac_f32_e32 v140, v2, v2
	v_fmac_f32_e32 v141, v3, v3
	v_fmac_f32_e32 v140, v4, v4
	v_fmac_f32_e32 v141, v5, v5
	v_fmac_f32_e32 v140, v6, v6
	v_fmac_f32_e32 v141, v7, v7
	v_fmac_f32_e32 v140, v8, v8
	v_fmac_f32_e32 v141, v9, v9
	v_fmac_f32_e32 v140, v10, v10
	v_fmac_f32_e32 v141, v11, v11
	v_fmac_f32_e32 v140, v12, v12
	v_fmac_f32_e32 v141, v13, v13
	v_fmac_f32_e32 v140, v14, v14
	v_fmac_f32_e32 v141, v15, v15
	v_fmac_f32_e32 v140, v16, v16
	v_fmac_f32_e32 v141, v17, v17
	v_fmac_f32_e32 v140, v18, v18
	v_fmac_f32_e32 v141, v19, v19
	v_fmac_f32_e32 v140, v20, v20
	v_fmac_f32_e32 v141, v21, v21
	v_fmac_f32_e32 v140, v22, v22
	v_fmac_f32_e32 v141, v23, v23
	v_fmac_f32_e32 v140, v24, v24
	v_fmac_f32_e32 v141, v25, v25
	v_fmac_f32_e32 v140, v26, v26
	v_fmac_f32_e32 v141, v27, v27
	v_fmac_f32_e32 v140, v28, v28
	v_fmac_f32_e32 v141, v29, v29
	v_fmac_f32_e32 v140, v30, v30
	v_fmac_f32_e32 v141, v31, v31
	v_add_f32_e32 v140, v140, v141
	s_nop 1
	v_add_f32_dpp v142, v140, v140 quad_perm:[1,0,3,2] row_mask:0xf bank_mask:0xf
	s_nop 1
	v_add_f32_dpp v142, v142, v142 quad_perm:[2,3,0,1] row_mask:0xf bank_mask:0xf
	s_nop 1
	v_add_f32_dpp v142, v142, v142 row_half_mirror row_mask:0xf bank_mask:0xf
	s_nop 1
	v_add_f32_dpp v142, v142, v142 row_mirror row_mask:0xf bank_mask:0xf
	s_nop 1
	v_readlane_b32 s20, v142, 0
	v_readlane_b32 s21, v142, 16
	v_readlane_b32 s22, v142, 32
	v_readlane_b32 s23, v142, 48
	s_nop 1
	v_mov_b32_e32 v143, s20
	v_add_f32_e32 v143, s21, v143
	v_add_f32_e32 v143, s22, v143
	v_add_f32_e32 v143, s23, v143
	v_fmamk_f32 v143, v143, 0x3a000000, v131
	v_rsq_f32_e32 v143, v143
	s_nop 0
	s_add_i32 s4, s6, 6
	s_lshl_b32 s5, s4, 12
	s_add_u32 s14, s84, s5
	s_addc_u32 s15, s85, 0
	s_add_u32 s14, s14, 0x1a800000
	s_addc_u32 s15, s15, 0
	v_mul_f32_e32 v136, v143, v0
	v_mul_f32_e32 v137, v143, v1
	v_mul_f32_e32 v138, v143, v2
	v_mul_f32_e32 v139, v143, v3
	v_fma_f32 v136, v136, v64, v96
	v_fma_f32 v137, v137, v65, v97
	v_fma_f32 v138, v138, v66, v98
	v_fma_f32 v139, v139, v67, v99
	v_cvt_pk_bf16_f32 v132, v136, v137
	v_cvt_pk_bf16_f32 v133, v138, v139
	global_store_dwordx2 v130, v[132:133], s[14:15] offset:0
	v_mul_f32_e32 v136, v143, v4
	v_mul_f32_e32 v137, v143, v5
	v_mul_f32_e32 v138, v143, v6
	v_mul_f32_e32 v139, v143, v7
	v_fma_f32 v136, v136, v68, v100
	v_fma_f32 v137, v137, v69, v101
	v_fma_f32 v138, v138, v70, v102
	v_fma_f32 v139, v139, v71, v103
	v_cvt_pk_bf16_f32 v134, v136, v137
	v_cvt_pk_bf16_f32 v135, v138, v139
	global_store_dwordx2 v130, v[134:135], s[14:15] offset:512
	v_mul_f32_e32 v136, v143, v8
	v_mul_f32_e32 v137, v143, v9
	v_mul_f32_e32 v138, v143, v10
	v_mul_f32_e32 v139, v143, v11
	v_fma_f32 v136, v136, v72, v104
	v_fma_f32 v137, v137, v73, v105
	v_fma_f32 v138, v138, v74, v106
	v_fma_f32 v139, v139, v75, v107
	v_cvt_pk_bf16_f32 v132, v136, v137
	v_cvt_pk_bf16_f32 v133, v138, v139
	global_store_dwordx2 v130, v[132:133], s[14:15] offset:1024
	v_mul_f32_e32 v136, v143, v12
	v_mul_f32_e32 v137, v143, v13
	v_mul_f32_e32 v138, v143, v14
	v_mul_f32_e32 v139, v143, v15
	v_fma_f32 v136, v136, v76, v108
	v_fma_f32 v137, v137, v77, v109
	v_fma_f32 v138, v138, v78, v110
	v_fma_f32 v139, v139, v79, v111
	v_cvt_pk_bf16_f32 v134, v136, v137
	v_cvt_pk_bf16_f32 v135, v138, v139
	global_store_dwordx2 v130, v[134:135], s[14:15] offset:1536
	v_mul_f32_e32 v136, v143, v16
	v_mul_f32_e32 v137, v143, v17
	v_mul_f32_e32 v138, v143, v18
	v_mul_f32_e32 v139, v143, v19
	v_fma_f32 v136, v136, v80, v112
	v_fma_f32 v137, v137, v81, v113
	v_fma_f32 v138, v138, v82, v114
	v_fma_f32 v139, v139, v83, v115
	v_cvt_pk_bf16_f32 v132, v136, v137
	v_cvt_pk_bf16_f32 v133, v138, v139
	global_store_dwordx2 v130, v[132:133], s[14:15] offset:2048
	v_mul_f32_e32 v136, v143, v20
	v_mul_f32_e32 v137, v143, v21
	v_mul_f32_e32 v138, v143, v22
	v_mul_f32_e32 v139, v143, v23
	v_fma_f32 v136, v136, v84, v116
	v_fma_f32 v137, v137, v85, v117
	v_fma_f32 v138, v138, v86, v118
	v_fma_f32 v139, v139, v87, v119
	v_cvt_pk_bf16_f32 v134, v136, v137
	v_cvt_pk_bf16_f32 v135, v138, v139
	global_store_dwordx2 v130, v[134:135], s[14:15] offset:2560
	v_mul_f32_e32 v136, v143, v24
	v_mul_f32_e32 v137, v143, v25
	v_mul_f32_e32 v138, v143, v26
	v_mul_f32_e32 v139, v143, v27
	v_fma_f32 v136, v136, v88, v120
	v_fma_f32 v137, v137, v89, v121
	v_fma_f32 v138, v138, v90, v122
	v_fma_f32 v139, v139, v91, v123
	v_cvt_pk_bf16_f32 v132, v136, v137
	v_cvt_pk_bf16_f32 v133, v138, v139
	global_store_dwordx2 v130, v[132:133], s[14:15] offset:3072
	v_mul_f32_e32 v136, v143, v28
	v_mul_f32_e32 v137, v143, v29
	v_mul_f32_e32 v138, v143, v30
	v_mul_f32_e32 v139, v143, v31
	v_fma_f32 v136, v136, v92, v124
	v_fma_f32 v137, v137, v93, v125
	v_fma_f32 v138, v138, v94, v126
	v_fma_f32 v139, v139, v95, v127
	v_cvt_pk_bf16_f32 v134, v136, v137
	v_cvt_pk_bf16_f32 v135, v138, v139
	global_store_dwordx2 v130, v[134:135], s[14:15] offset:3584
	s_add_i32 s4, s6, 8
	s_cmp_lt_u32 s4, 0x4000
	s_cselect_b32 s10, s68, s72
	s_cselect_b32 s11, s69, s73
	s_cselect_b32 s5, 0, 0x4000
	s_sub_i32 s5, s4, s5
	s_lshl_b32 s5, s5, 13
	s_add_u32 s10, s10, s5
	s_addc_u32 s11, s11, 0
	global_load_dwordx4 v[0:3], v128, s[10:11] offset:0 nt
	global_load_dwordx4 v[4:7], v128, s[10:11] offset:1024 nt
	global_load_dwordx4 v[8:11], v128, s[10:11] offset:2048 nt
	global_load_dwordx4 v[12:15], v128, s[10:11] offset:3072 nt
	global_load_dwordx4 v[16:19], v129, s[10:11] offset:0 nt
	global_load_dwordx4 v[20:23], v129, s[10:11] offset:1024 nt
	global_load_dwordx4 v[24:27], v129, s[10:11] offset:2048 nt
	global_load_dwordx4 v[28:31], v129, s[10:11] offset:3072 nt
	s_add_i32 s4, s6, 7
	s_add_i32 s4, s6, 7
	s_lshr_b32 s8, s4, 11
	s_cmp_lt_u32 s4, 0x4000
	s_cselect_b32 s8, s8, 8
	s_cmp_eq_u32 s8, s7
	s_cbranch_scc1 .Lp1_np7
; __device__ __forceinline__ unsigned cvt_pk_bf16(float lo, float hi) { unsigned r; asm volatile("v_cvt_pk_bf16_f32 %0, %1, %2" : "=v"(r) : "v"(lo), "v"(hi)); return r; }
; __device__ __forceinline__ void modulate_store(const f32x4 (&v)[8], float rstd, const float* pn, const float* modr, bf16_t* orow, int lane) {
; #pragma unroll
;     for (int j = 0; j < 8; ++j) { const int col = 4 * lane + 256 * j;
;         const f32x4 g = *(const f32x4*)(pn + col), sh = *(const f32x4*)(modr + col), sc = *(const f32x4*)(modr + DM + col);
;         const f32x4 hh = v[j] * rstd * g * (sc + 1.f) + sh;
;         u32x2 w; w.x = cvt_pk_bf16(hh[0], hh[1]); w.y = cvt_pk_bf16(hh[2], hh[3]);
;         *(u32x2*)(orow + col) = w; }
; __global__ void __launch_bounds__(NWAVES * 64, 2) mk_fwd(Args args) {
;     ...
;             for (int q = 0; q < 3; ++q) { const int row = row0 + q; const int r = row < ML ? row / SEQ : 8;
;                 const float rstd = __builtin_amdgcn_rsqf(sumsq8(v[q]) * (1.f / DM) + EPS);
	s_mov_b32 s7, s8
	s_add_i32 s5, s8, 0
	s_mul_i32 s5, s5, 0x6000
	s_add_u32 s24, s84, s5
	s_addc_u32 s25, s85, 0
	s_add_u32 s24, s24, 0x2000
	s_addc_u32 s25, s25, 0
	s_add_i32 s5, s8, 0
	s_mul_i32 s5, s5, 0x6000
	s_add_u32 s16, s84, s5
	s_addc_u32 s17, s85, 0
	s_add_u32 s18, s80, 0x0
	s_addc_u32 s19, s81, 0
	global_load_dwordx4 v[64:67], v128, s[18:19] offset:0
	global_load_dwordx4 v[96:99], v128, s[16:17] offset:0
	global_load_dwordx4 v[68:71], v128, s[18:19] offset:1024
	global_load_dwordx4 v[100:103], v128, s[16:17] offset:1024
	global_load_dwordx4 v[72:75], v128, s[18:19] offset:2048
	global_load_dwordx4 v[104:107], v128, s[16:17] offset:2048
	global_load_dwordx4 v[76:79], v128, s[18:19] offset:3072
	global_load_dwordx4 v[108:111], v128, s[16:17] offset:3072
	global_load_dwordx4 v[80:83], v129, s[18:19] offset:0
	global_load_dwordx4 v[112:115], v129, s[16:17] offset:0
	global_load_dwordx4 v[84:87], v129, s[18:19] offset:1024
	global_load_dwordx4 v[116:119], v129, s[16:17] offset:1024
	global_load_dwordx4 v[88:91], v129, s[18:19] offset:2048
	global_load_dwordx4 v[120:123], v129, s[16:17] offset:2048
	global_load_dwordx4 v[92:95], v129, s[18:19] offset:3072
	global_load_dwordx4 v[124:127], v129, s[16:17] offset:3072
	global_load_dwordx4 v[136:139], v128, s[24:25] offset:0
	s_waitcnt vmcnt(0)
	v_add_f32_e32 v136, 1.0, v136
	v_add_f32_e32 v137, 1.0, v137
	v_add_f32_e32 v138, 1.0, v138
	v_add_f32_e32 v139, 1.0, v139
	v_mul_f32_e32 v64, v64, v136
	v_mul_f32_e32 v65, v65, v137
	v_mul_f32_e32 v66, v66, v138
	v_mul_f32_e32 v67, v67, v139
	global_load_dwordx4 v[136:139], v128, s[24:25] offset:1024
	s_waitcnt vmcnt(0)
	v_add_f32_e32 v136, 1.0, v136
	v_add_f32_e32 v137, 1.0, v137
	v_add_f32_e32 v138, 1.0, v138
	v_add_f32_e32 v139, 1.0, v139
	v_mul_f32_e32 v68, v68, v136
	v_mul_f32_e32 v69, v69, v137
	v_mul_f32_e32 v70, v70, v138
	v_mul_f32_e32 v71, v71, v139
	global_load_dwordx4 v[136:139], v128, s[24:25] offset:2048
	s_waitcnt vmcnt(0)
	v_add_f32_e32 v136, 1.0, v136
	v_add_f32_e32 v137, 1.0, v137
	v_add_f32_e32 v138, 1.0, v138
	v_add_f32_e32 v139, 1.0, v139
	v_mul_f32_e32 v72, v72, v136
	v_mul_f32_e32 v73, v73, v137
	v_mul_f32_e32 v74, v74, v138
	v_mul_f32_e32 v75, v75, v139
	global_load_dwordx4 v[136:139], v128, s[24:25] offset:3072
	s_waitcnt vmcnt(0)
	v_add_f32_e32 v136, 1.0, v136
	v_add_f32_e32 v137, 1.0, v137
	v_add_f32_e32 v138, 1.0, v138
	v_add_f32_e32 v139, 1.0, v139
	v_mul_f32_e32 v76, v76, v136
	v_mul_f32_e32 v77, v77, v137
	v_mul_f32_e32 v78, v78, v138
	v_mul_f32_e32 v79, v79, v139
	global_load_dwordx4 v[136:139], v129, s[24:25] offset:0
	s_waitcnt vmcnt(0)
	v_add_f32_e32 v136, 1.0, v136
	v_add_f32_e32 v137, 1.0, v137
	v_add_f32_e32 v138, 1.0, v138
	v_add_f32_e32 v139, 1.0, v139
	v_mul_f32_e32 v80, v80, v136
	v_mul_f32_e32 v81, v81, v137
	v_mul_f32_e32 v82, v82, v138
	v_mul_f32_e32 v83, v83, v139
	global_load_dwordx4 v[136:139], v129, s[24:25] offset:1024
	s_waitcnt vmcnt(0)
	v_add_f32_e32 v136, 1.0, v136
	v_add_f32_e32 v137, 1.0, v137
	v_add_f32_e32 v138, 1.0, v138
	v_add_f32_e32 v139, 1.0, v139
	v_mul_f32_e32 v84, v84, v136
	v_mul_f32_e32 v85, v85, v137
	v_mul_f32_e32 v86, v86, v138
	v_mul_f32_e32 v87, v87, v139
	global_load_dwordx4 v[136:139], v129, s[24:25] offset:2048
	s_waitcnt vmcnt(0)
	v_add_f32_e32 v136, 1.0, v136
	v_add_f32_e32 v137, 1.0, v137
	v_add_f32_e32 v138, 1.0, v138
	v_add_f32_e32 v139, 1.0, v139
	v_mul_f32_e32 v88, v88, v136
	v_mul_f32_e32 v89, v89, v137
	v_mul_f32_e32 v90, v90, v138
	v_mul_f32_e32 v91, v91, v139
	global_load_dwordx4 v[136:139], v129, s[24:25] offset:3072
	s_waitcnt vmcnt(0)
	v_add_f32_e32 v136, 1.0, v136
	v_add_f32_e32 v137, 1.0, v137
	v_add_f32_e32 v138, 1.0, v138
	v_add_f32_e32 v139, 1.0, v139
	v_mul_f32_e32 v92, v92, v136
	v_mul_f32_e32 v93, v93, v137
	v_mul_f32_e32 v94, v94, v138
	v_mul_f32_e32 v95, v95, v139
.Lp1_np7:
	s_waitcnt vmcnt(16)
	v_mul_f32_e32 v140, v32, v32
	v_mul_f32_e32 v141, v33, v33
	v_fmac_f32_e32 v140, v34, v34
	v_fmac_f32_e32 v141, v35, v35
	v_fmac_f32_e32 v140, v36, v36
	v_fmac_f32_e32 v141, v37, v37
	v_fmac_f32_e32 v140, v38, v38
	v_fmac_f32_e32 v141, v39, v39
	v_fmac_f32_e32 v140, v40, v40
	v_fmac_f32_e32 v141, v41, v41
	v_fmac_f32_e32 v140, v42, v42
	v_fmac_f32_e32 v141, v43, v43
	v_fmac_f32_e32 v140, v44, v44
	v_fmac_f32_e32 v141, v45, v45
	v_fmac_f32_e32 v140, v46, v46
	v_fmac_f32_e32 v141, v47, v47
	v_fmac_f32_e32 v140, v48, v48
	v_fmac_f32_e32 v141, v49, v49
	v_fmac_f32_e32 v140, v50, v50
	v_fmac_f32_e32 v141, v51, v51
	v_fmac_f32_e32 v140, v52, v52
	v_fmac_f32_e32 v141, v53, v53
	v_fmac_f32_e32 v140, v54, v54
	v_fmac_f32_e32 v141, v55, v55
	v_fmac_f32_e32 v140, v56, v56
	v_fmac_f32_e32 v141, v57, v57
	v_fmac_f32_e32 v140, v58, v58
	v_fmac_f32_e32 v141, v59, v59
	v_fmac_f32_e32 v140, v60, v60
	v_fmac_f32_e32 v141, v61, v61
	v_fmac_f32_e32 v140, v62, v62
	v_fmac_f32_e32 v141, v63, v63
	v_add_f32_e32 v140, v140, v141
	s_nop 1
	v_add_f32_dpp v142, v140, v140 quad_perm:[1,0,3,2] row_mask:0xf bank_mask:0xf
	s_nop 1
	v_add_f32_dpp v142, v142, v142 quad_perm:[2,3,0,1] row_mask:0xf bank_mask:0xf
	s_nop 1
	v_add_f32_dpp v142, v142, v142 row_half_mirror row_mask:0xf bank_mask:0xf
	s_nop 1
	v_add_f32_dpp v142, v142, v142 row_mirror row_mask:0xf bank_mask:0xf
	s_nop 1
	v_readlane_b32 s20, v142, 0
	v_readlane_b32 s21, v142, 16
	v_readlane_b32 s22, v142, 32
	v_readlane_b32 s23, v142, 48
	s_nop 1
	v_mov_b32_e32 v143, s20
	v_add_f32_e32 v143, s21, v143
	v_add_f32_e32 v143, s22, v143
	v_add_f32_e32 v143, s23, v143
	v_fmamk_f32 v143, v143, 0x3a000000, v131
	v_rsq_f32_e32 v143, v143
	s_nop 0
	s_add_i32 s4, s6, 7
	s_lshl_b32 s5, s4, 12
	s_add_u32 s14, s84, s5
	s_addc_u32 s15, s85, 0
; __device__ __forceinline__ unsigned cvt_pk_bf16(float lo, float hi) { unsigned r; asm volatile("v_cvt_pk_bf16_f32 %0, %1, %2" : "=v"(r) : "v"(lo), "v"(hi)); return r; }
; __device__ __forceinline__ void modulate_store(const f32x4 (&v)[8], float rstd, const float* pn, const float* modr, bf16_t* orow, int lane) {
; #pragma unroll
;     for (int j = 0; j < 8; ++j) { const int col = 4 * lane + 256 * j;
;         const f32x4 g = *(const f32x4*)(pn + col), sh = *(const f32x4*)(modr + col), sc = *(const f32x4*)(modr + DM + col);
;         const f32x4 hh = v[j] * rstd * g * (sc + 1.f) + sh;
;         u32x2 w; w.x = cvt_pk_bf16(hh[0], hh[1]); w.y = cvt_pk_bf16(hh[2], hh[3]);
;         *(u32x2*)(orow + col) = w; }
; __global__ void __launch_bounds__(NWAVES * 64, 2) mk_fwd(Args args) {
;     ...
;             for (int q = 0; q < 3; ++q) { const int row = row0 + q; const int r = row < ML ? row / SEQ : 8;
;                 const float rstd = __builtin_amdgcn_rsqf(sumsq8(v[q]) * (1.f / DM) + EPS);
	s_add_u32 s14, s14, 0x1a800000
	s_addc_u32 s15, s15, 0
	v_mul_f32_e32 v136, v143, v32
	v_mul_f32_e32 v137, v143, v33
	v_mul_f32_e32 v138, v143, v34
	v_mul_f32_e32 v139, v143, v35
	v_fma_f32 v136, v136, v64, v96
	v_fma_f32 v137, v137, v65, v97
	v_fma_f32 v138, v138, v66, v98
	v_fma_f32 v139, v139, v67, v99
	v_cvt_pk_bf16_f32 v132, v136, v137
	v_cvt_pk_bf16_f32 v133, v138, v139
	global_store_dwordx2 v130, v[132:133], s[14:15] offset:0
	v_mul_f32_e32 v136, v143, v36
	v_mul_f32_e32 v137, v143, v37
	v_mul_f32_e32 v138, v143, v38
	v_mul_f32_e32 v139, v143, v39
	v_fma_f32 v136, v136, v68, v100
	v_fma_f32 v137, v137, v69, v101
	v_fma_f32 v138, v138, v70, v102
	v_fma_f32 v139, v139, v71, v103
	v_cvt_pk_bf16_f32 v134, v136, v137
	v_cvt_pk_bf16_f32 v135, v138, v139
	global_store_dwordx2 v130, v[134:135], s[14:15] offset:512
	v_mul_f32_e32 v136, v143, v40
	v_mul_f32_e32 v137, v143, v41
	v_mul_f32_e32 v138, v143, v42
	v_mul_f32_e32 v139, v143, v43
	v_fma_f32 v136, v136, v72, v104
	v_fma_f32 v137, v137, v73, v105
	v_fma_f32 v138, v138, v74, v106
	v_fma_f32 v139, v139, v75, v107
	v_cvt_pk_bf16_f32 v132, v136, v137
	v_cvt_pk_bf16_f32 v133, v138, v139
	global_store_dwordx2 v130, v[132:133], s[14:15] offset:1024
	v_mul_f32_e32 v136, v143, v44
	v_mul_f32_e32 v137, v143, v45
	v_mul_f32_e32 v138, v143, v46
	v_mul_f32_e32 v139, v143, v47
	v_fma_f32 v136, v136, v76, v108
	v_fma_f32 v137, v137, v77, v109
	v_fma_f32 v138, v138, v78, v110
	v_fma_f32 v139, v139, v79, v111
	v_cvt_pk_bf16_f32 v134, v136, v137
	v_cvt_pk_bf16_f32 v135, v138, v139
	global_store_dwordx2 v130, v[134:135], s[14:15] offset:1536
	v_mul_f32_e32 v136, v143, v48
	v_mul_f32_e32 v137, v143, v49
	v_mul_f32_e32 v138, v143, v50
	v_mul_f32_e32 v139, v143, v51
	v_fma_f32 v136, v136, v80, v112
	v_fma_f32 v137, v137, v81, v113
	v_fma_f32 v138, v138, v82, v114
	v_fma_f32 v139, v139, v83, v115
	v_cvt_pk_bf16_f32 v132, v136, v137
	v_cvt_pk_bf16_f32 v133, v138, v139
	global_store_dwordx2 v130, v[132:133], s[14:15] offset:2048
	v_mul_f32_e32 v136, v143, v52
	v_mul_f32_e32 v137, v143, v53
	v_mul_f32_e32 v138, v143, v54
	v_mul_f32_e32 v139, v143, v55
	v_fma_f32 v136, v136, v84, v116
	v_fma_f32 v137, v137, v85, v117
	v_fma_f32 v138, v138, v86, v118
	v_fma_f32 v139, v139, v87, v119
	v_cvt_pk_bf16_f32 v134, v136, v137
	v_cvt_pk_bf16_f32 v135, v138, v139
	global_store_dwordx2 v130, v[134:135], s[14:15] offset:2560
	v_mul_f32_e32 v136, v143, v56
	v_mul_f32_e32 v137, v143, v57
	v_mul_f32_e32 v138, v143, v58
	v_mul_f32_e32 v139, v143, v59
	v_fma_f32 v136, v136, v88, v120
	v_fma_f32 v137, v137, v89, v121
	v_fma_f32 v138, v138, v90, v122
	v_fma_f32 v139, v139, v91, v123
	v_cvt_pk_bf16_f32 v132, v136, v137
	v_cvt_pk_bf16_f32 v133, v138, v139
	global_store_dwordx2 v130, v[132:133], s[14:15] offset:3072
	v_mul_f32_e32 v136, v143, v60
	v_mul_f32_e32 v137, v143, v61
	v_mul_f32_e32 v138, v143, v62
	v_mul_f32_e32 v139, v143, v63
	v_fma_f32 v136, v136, v92, v124
	v_fma_f32 v137, v137, v93, v125
	v_fma_f32 v138, v138, v94, v126
	v_fma_f32 v139, v139, v95, v127
	v_cvt_pk_bf16_f32 v134, v136, v137
	v_cvt_pk_bf16_f32 v135, v138, v139
	global_store_dwordx2 v130, v[134:135], s[14:15] offset:3584
	s_add_i32 s4, s6, 8
	s_add_i32 s4, s6, 8
	s_lshr_b32 s8, s4, 11
	s_cmp_lt_u32 s4, 0x4000
	s_cselect_b32 s8, s8, 8
	s_cmp_eq_u32 s8, s7
	s_cbranch_scc1 .Lp1_np8
	s_mov_b32 s7, s8
	s_add_i32 s5, s8, 0
	s_mul_i32 s5, s5, 0x6000
	s_add_u32 s24, s84, s5
	s_addc_u32 s25, s85, 0
	s_add_u32 s24, s24, 0x2000
	s_addc_u32 s25, s25, 0
	s_add_i32 s5, s8, 0
	s_mul_i32 s5, s5, 0x6000
	s_add_u32 s16, s84, s5
	s_addc_u32 s17, s85, 0
	s_add_u32 s18, s80, 0x0
	s_addc_u32 s19, s81, 0
	global_load_dwordx4 v[64:67], v128, s[18:19] offset:0
	global_load_dwordx4 v[96:99], v128, s[16:17] offset:0
	global_load_dwordx4 v[68:71], v128, s[18:19] offset:1024
	global_load_dwordx4 v[100:103], v128, s[16:17] offset:1024
	global_load_dwordx4 v[72:75], v128, s[18:19] offset:2048
	global_load_dwordx4 v[104:107], v128, s[16:17] offset:2048
	global_load_dwordx4 v[76:79], v128, s[18:19] offset:3072
	global_load_dwordx4 v[108:111], v128, s[16:17] offset:3072
	global_load_dwordx4 v[80:83], v129, s[18:19] offset:0
	global_load_dwordx4 v[112:115], v129, s[16:17] offset:0
	global_load_dwordx4 v[84:87], v129, s[18:19] offset:1024
	global_load_dwordx4 v[116:119], v129, s[16:17] offset:1024
	global_load_dwordx4 v[88:91], v129, s[18:19] offset:2048
	global_load_dwordx4 v[120:123], v129, s[16:17] offset:2048
	global_load_dwordx4 v[92:95], v129, s[18:19] offset:3072
	global_load_dwordx4 v[124:127], v129, s[16:17] offset:3072
	global_load_dwordx4 v[136:139], v128, s[24:25] offset:0
	s_waitcnt vmcnt(0)
	v_add_f32_e32 v136, 1.0, v136
	v_add_f32_e32 v137, 1.0, v137
	v_add_f32_e32 v138, 1.0, v138
	v_add_f32_e32 v139, 1.0, v139
	v_mul_f32_e32 v64, v64, v136
	v_mul_f32_e32 v65, v65, v137
	v_mul_f32_e32 v66, v66, v138
	v_mul_f32_e32 v67, v67, v139
	global_load_dwordx4 v[136:139], v128, s[24:25] offset:1024
	s_waitcnt vmcnt(0)
	v_add_f32_e32 v136, 1.0, v136
	v_add_f32_e32 v137, 1.0, v137
	v_add_f32_e32 v138, 1.0, v138
	v_add_f32_e32 v139, 1.0, v139
	v_mul_f32_e32 v68, v68, v136
	v_mul_f32_e32 v69, v69, v137
	v_mul_f32_e32 v70, v70, v138
	v_mul_f32_e32 v71, v71, v139
	global_load_dwordx4 v[136:139], v128, s[24:25] offset:2048
	s_waitcnt vmcnt(0)
	v_add_f32_e32 v136, 1.0, v136
	v_add_f32_e32 v137, 1.0, v137
	v_add_f32_e32 v138, 1.0, v138
	v_add_f32_e32 v139, 1.0, v139
	v_mul_f32_e32 v72, v72, v136
	v_mul_f32_e32 v73, v73, v137
	v_mul_f32_e32 v74, v74, v138
	v_mul_f32_e32 v75, v75, v139
	global_load_dwordx4 v[136:139], v128, s[24:25] offset:3072
	s_waitcnt vmcnt(0)
; __device__ __forceinline__ unsigned cvt_pk_bf16(float lo, float hi) { unsigned r; asm volatile("v_cvt_pk_bf16_f32 %0, %1, %2" : "=v"(r) : "v"(lo), "v"(hi)); return r; }
; __device__ __forceinline__ float sumsq8(const f32x4 (&v)[8]) {
;     float s = 0.f;
; #pragma unroll
;     for (int j = 0; j < 8; ++j) s += (v[j][0] * v[j][0] + v[j][1] * v[j][1]) + (v[j][2] * v[j][2] + v[j][3] * v[j][3]);
;     return wave_sum(s);
; }
; __device__ __forceinline__ void modulate_store(const f32x4 (&v)[8], float rstd, const float* pn, const float* modr, bf16_t* orow, int lane) {
; #pragma unroll
;     for (int j = 0; j < 8; ++j) { const int col = 4 * lane + 256 * j;
;         const f32x4 g = *(const f32x4*)(pn + col), sh = *(const f32x4*)(modr + col), sc = *(const f32x4*)(modr + DM + col);
;         const f32x4 hh = v[j] * rstd * g * (sc + 1.f) + sh;
;         u32x2 w; w.x = cvt_pk_bf16(hh[0], hh[1]); w.y = cvt_pk_bf16(hh[2], hh[3]);
;         *(u32x2*)(orow + col) = w; }
; __global__ void __launch_bounds__(NWAVES * 64, 2) mk_fwd(Args args) {
;     ...
;             for (int q = 0; q < 3; ++q) { const int row = row0 + q; const int r = row < ML ? row / SEQ : 8;
;                 const float rstd = __builtin_amdgcn_rsqf(sumsq8(v[q]) * (1.f / DM) + EPS);
;                 modulate_store(v[q], rstd, pre_norm, mod + (size_t)r * 6144, H + (size_t)row * DM, F.lane); }
	v_add_f32_e32 v136, 1.0, v136
	v_add_f32_e32 v137, 1.0, v137
	v_add_f32_e32 v138, 1.0, v138
	v_add_f32_e32 v139, 1.0, v139
	v_mul_f32_e32 v76, v76, v136
	v_mul_f32_e32 v77, v77, v137
	v_mul_f32_e32 v78, v78, v138
	v_mul_f32_e32 v79, v79, v139
	global_load_dwordx4 v[136:139], v129, s[24:25] offset:0
	s_waitcnt vmcnt(0)
	v_add_f32_e32 v136, 1.0, v136
	v_add_f32_e32 v137, 1.0, v137
	v_add_f32_e32 v138, 1.0, v138
	v_add_f32_e32 v139, 1.0, v139
	v_mul_f32_e32 v80, v80, v136
	v_mul_f32_e32 v81, v81, v137
	v_mul_f32_e32 v82, v82, v138
	v_mul_f32_e32 v83, v83, v139
	global_load_dwordx4 v[136:139], v129, s[24:25] offset:1024
	s_waitcnt vmcnt(0)
	v_add_f32_e32 v136, 1.0, v136
	v_add_f32_e32 v137, 1.0, v137
	v_add_f32_e32 v138, 1.0, v138
	v_add_f32_e32 v139, 1.0, v139
	v_mul_f32_e32 v84, v84, v136
	v_mul_f32_e32 v85, v85, v137
	v_mul_f32_e32 v86, v86, v138
	v_mul_f32_e32 v87, v87, v139
	global_load_dwordx4 v[136:139], v129, s[24:25] offset:2048
	s_waitcnt vmcnt(0)
	v_add_f32_e32 v136, 1.0, v136
	v_add_f32_e32 v137, 1.0, v137
	v_add_f32_e32 v138, 1.0, v138
	v_add_f32_e32 v139, 1.0, v139
	v_mul_f32_e32 v88, v88, v136
	v_mul_f32_e32 v89, v89, v137
	v_mul_f32_e32 v90, v90, v138
	v_mul_f32_e32 v91, v91, v139
	global_load_dwordx4 v[136:139], v129, s[24:25] offset:3072
	s_waitcnt vmcnt(0)
	v_add_f32_e32 v136, 1.0, v136
	v_add_f32_e32 v137, 1.0, v137
	v_add_f32_e32 v138, 1.0, v138
	v_add_f32_e32 v139, 1.0, v139
	v_mul_f32_e32 v92, v92, v136
	v_mul_f32_e32 v93, v93, v137
	v_mul_f32_e32 v94, v94, v138
	v_mul_f32_e32 v95, v95, v139
.Lp1_np8:
	s_waitcnt vmcnt(8)
	v_mul_f32_e32 v140, v0, v0
	v_mul_f32_e32 v141, v1, v1
	v_fmac_f32_e32 v140, v2, v2
	v_fmac_f32_e32 v141, v3, v3
	v_fmac_f32_e32 v140, v4, v4
	v_fmac_f32_e32 v141, v5, v5
	v_fmac_f32_e32 v140, v6, v6
	v_fmac_f32_e32 v141, v7, v7
	v_fmac_f32_e32 v140, v8, v8
	v_fmac_f32_e32 v141, v9, v9
	v_fmac_f32_e32 v140, v10, v10
	v_fmac_f32_e32 v141, v11, v11
	v_fmac_f32_e32 v140, v12, v12
	v_fmac_f32_e32 v141, v13, v13
	v_fmac_f32_e32 v140, v14, v14
	v_fmac_f32_e32 v141, v15, v15
	v_fmac_f32_e32 v140, v16, v16
	v_fmac_f32_e32 v141, v17, v17
	v_fmac_f32_e32 v140, v18, v18
	v_fmac_f32_e32 v141, v19, v19
	v_fmac_f32_e32 v140, v20, v20
	v_fmac_f32_e32 v141, v21, v21
	v_fmac_f32_e32 v140, v22, v22
	v_fmac_f32_e32 v141, v23, v23
	v_fmac_f32_e32 v140, v24, v24
	v_fmac_f32_e32 v141, v25, v25
	v_fmac_f32_e32 v140, v26, v26
	v_fmac_f32_e32 v141, v27, v27
	v_fmac_f32_e32 v140, v28, v28
	v_fmac_f32_e32 v141, v29, v29
	v_fmac_f32_e32 v140, v30, v30
	v_fmac_f32_e32 v141, v31, v31
	v_add_f32_e32 v140, v140, v141
	s_nop 1
	v_add_f32_dpp v142, v140, v140 quad_perm:[1,0,3,2] row_mask:0xf bank_mask:0xf
	s_nop 1
	v_add_f32_dpp v142, v142, v142 quad_perm:[2,3,0,1] row_mask:0xf bank_mask:0xf
	s_nop 1
	v_add_f32_dpp v142, v142, v142 row_half_mirror row_mask:0xf bank_mask:0xf
	s_nop 1
	v_add_f32_dpp v142, v142, v142 row_mirror row_mask:0xf bank_mask:0xf
	s_nop 1
	v_readlane_b32 s20, v142, 0
	v_readlane_b32 s21, v142, 16
	v_readlane_b32 s22, v142, 32
	v_readlane_b32 s23, v142, 48
	s_nop 1
	v_mov_b32_e32 v143, s20
	v_add_f32_e32 v143, s21, v143
	v_add_f32_e32 v143, s22, v143
	v_add_f32_e32 v143, s23, v143
	v_fmamk_f32 v143, v143, 0x3a000000, v131
	v_rsq_f32_e32 v143, v143
	s_nop 0
	s_add_i32 s4, s6, 8
	s_lshl_b32 s5, s4, 12
	s_add_u32 s14, s84, s5
	s_addc_u32 s15, s85, 0
	s_add_u32 s14, s14, 0x1a800000
	s_addc_u32 s15, s15, 0
	v_mul_f32_e32 v136, v143, v0
	v_mul_f32_e32 v137, v143, v1
	v_mul_f32_e32 v138, v143, v2
	v_mul_f32_e32 v139, v143, v3
	v_fma_f32 v136, v136, v64, v96
	v_fma_f32 v137, v137, v65, v97
	v_fma_f32 v138, v138, v66, v98
	v_fma_f32 v139, v139, v67, v99
	v_cvt_pk_bf16_f32 v132, v136, v137
	v_cvt_pk_bf16_f32 v133, v138, v139
	global_store_dwordx2 v130, v[132:133], s[14:15] offset:0
	v_mul_f32_e32 v136, v143, v4
	v_mul_f32_e32 v137, v143, v5
	v_mul_f32_e32 v138, v143, v6
	v_mul_f32_e32 v139, v143, v7
	v_fma_f32 v136, v136, v68, v100
	v_fma_f32 v137, v137, v69, v101
	v_fma_f32 v138, v138, v70, v102
	v_fma_f32 v139, v139, v71, v103
	v_cvt_pk_bf16_f32 v134, v136, v137
	v_cvt_pk_bf16_f32 v135, v138, v139
	global_store_dwordx2 v130, v[134:135], s[14:15] offset:512
	v_mul_f32_e32 v136, v143, v8
	v_mul_f32_e32 v137, v143, v9
	v_mul_f32_e32 v138, v143, v10
	v_mul_f32_e32 v139, v143, v11
	v_fma_f32 v136, v136, v72, v104
	v_fma_f32 v137, v137, v73, v105
	v_fma_f32 v138, v138, v74, v106
	v_fma_f32 v139, v139, v75, v107
	v_cvt_pk_bf16_f32 v132, v136, v137
	v_cvt_pk_bf16_f32 v133, v138, v139
	global_store_dwordx2 v130, v[132:133], s[14:15] offset:1024
	v_mul_f32_e32 v136, v143, v12
	v_mul_f32_e32 v137, v143, v13
	v_mul_f32_e32 v138, v143, v14
	v_mul_f32_e32 v139, v143, v15
	v_fma_f32 v136, v136, v76, v108
	v_fma_f32 v137, v137, v77, v109
	v_fma_f32 v138, v138, v78, v110
	v_fma_f32 v139, v139, v79, v111
	v_cvt_pk_bf16_f32 v134, v136, v137
	v_cvt_pk_bf16_f32 v135, v138, v139
	global_store_dwordx2 v130, v[134:135], s[14:15] offset:1536
	v_mul_f32_e32 v136, v143, v16
	v_mul_f32_e32 v137, v143, v17
	v_mul_f32_e32 v138, v143, v18
	v_mul_f32_e32 v139, v143, v19
	v_fma_f32 v136, v136, v80, v112
	v_fma_f32 v137, v137, v81, v113
	v_fma_f32 v138, v138, v82, v114
	v_fma_f32 v139, v139, v83, v115
	v_cvt_pk_bf16_f32 v132, v136, v137
	v_cvt_pk_bf16_f32 v133, v138, v139
	global_store_dwordx2 v130, v[132:133], s[14:15] offset:2048
	v_mul_f32_e32 v136, v143, v20
	v_mul_f32_e32 v137, v143, v21
	v_mul_f32_e32 v138, v143, v22
	v_mul_f32_e32 v139, v143, v23
	v_fma_f32 v136, v136, v84, v116
	v_fma_f32 v137, v137, v85, v117
	v_fma_f32 v138, v138, v86, v118
	v_fma_f32 v139, v139, v87, v119
	v_cvt_pk_bf16_f32 v134, v136, v137
	v_cvt_pk_bf16_f32 v135, v138, v139
	global_store_dwordx2 v130, v[134:135], s[14:15] offset:2560
	v_mul_f32_e32 v136, v143, v24
	v_mul_f32_e32 v137, v143, v25
	v_mul_f32_e32 v138, v143, v26
	v_mul_f32_e32 v139, v143, v27
	v_fma_f32 v136, v136, v88, v120
	v_fma_f32 v137, v137, v89, v121
	v_fma_f32 v138, v138, v90, v122
	v_fma_f32 v139, v139, v91, v123
	v_cvt_pk_bf16_f32 v132, v136, v137
	v_cvt_pk_bf16_f32 v133, v138, v139
	global_store_dwordx2 v130, v[132:133], s[14:15] offset:3072
	v_mul_f32_e32 v136, v143, v28
	v_mul_f32_e32 v137, v143, v29
	v_mul_f32_e32 v138, v143, v30
	v_mul_f32_e32 v139, v143, v31
	v_fma_f32 v136, v136, v92, v124
	v_fma_f32 v137, v137, v93, v125
	v_fma_f32 v138, v138, v94, v126
	v_fma_f32 v139, v139, v95, v127
	v_cvt_pk_bf16_f32 v134, v136, v137
	v_cvt_pk_bf16_f32 v135, v138, v139
	global_store_dwordx2 v130, v[134:135], s[14:15] offset:3584
	s_branch .LBB0_194

; __global__ void __launch_bounds__(NWAVES * 64, 2) mk_fwd(Args args) {
;     ...
;     if (IN(2)) {
;         pg8::Gemm g{H, WIN, MT, 4096, DM, DM, DM, 0}; pg8::StaticOrder S; S.init(MT, 4096, F.G, (int)blockIdx.x);
;         pg8::EpiPoolIn E{U, SG};
;         pg8::gemm_phase<pg8::EpiPoolIn>(F.lds, g, S, E);
.LBB0_244:
	s_cmpk_lg_i32 s63, 0x100
	s_cbranch_scc1 .Lh0reloc_skip
	s_add_u32 s12, s84, 0x1a800000
	s_addc_u32 s13, s85, 0
